# NA: V pack with v_perm_b32 + out-of-place dword rotation; P pack with v_cvt_pk_bf16_f32 where liveness allows
# speedup vs baseline: 1.0755x; 1.0008x over previous
; __device__ __forceinline__ void na2_task(const Params& p_, int l, int task, unsigned char* lds) {
;     ...
;     { const int pair = lane & 31, chunk = (lane >> 5) + 2 * (w & 3);
;       unsigned* VTd = (unsigned*)(VT + (size_t)hh * 64 * 520);
;       u32x4 xs[8], ys[8];
; #pragma unroll
;       for (int a = 0; a < 8; ++a) { const size_t tok = (size_t)b * SEQ + (row_start + a) * 64 + 2 * pair;
;           const bf16* src = Z + tok * DIN + 4 * DG + h * 64 + chunk * 8; xs[a] = *(const u32x4*)src; ys[a] = *(const u32x4*)(src + DIN); }
;     ...
;             for (int i = 0; i < 8; ++i) { const int a = 4 + i / 2, ci = i % 2;
;                 const size_t ktok = (size_t)b * SEQ + (row_start + a) * 64 + kst + 16 * ci + fr;
; #pragma unroll
;                 for (int ks = 0; ks < 2; ++ks) kfr[i][ks] = *(const bf16x8v*)(Z + ktok * DIN + 3 * DG + h * 64 + 32 * ks + 8 * fq); }
.LBB0_385:
	v_bfe_u32 v172, v147, 2, 3
	v_bfe_u32 v249, v147, 6, 2
	v_lshl_or_b32 v172, v249, 3, v172
	v_lshl_or_b32 v88, v172, 1, s42
	v_or_b32_e32 v81, s24, v88
	v_mov_b64_e32 v[86:87], s[40:41]
	v_and_b32_e32 v173, 3, v147
	v_bfe_u32 v249, v147, 5, 1
	v_lshl_or_b32 v173, v249, 2, v173
	v_lshlrev_b32_e32 v173, 3, v173
	v_mad_u64_u32 v[94:95], s[40:41], v81, s75, v[86:87]
	v_mad_i32_i24 v95, s43, v195, v95
	v_mov_b32_e32 v89, s43
	v_lshl_add_u64 v[94:95], v[94:95], 0, v[76:77]
	v_lshlrev_b32_e32 v164, 1, v173
	v_mov_b32_e32 v165, v1
	v_lshl_add_u64 v[94:95], v[94:95], 0, v[164:165]
	v_lshl_add_u64 v[102:103], v[88:89], 0, s[44:45]
	v_add_co_u32_e32 v96, vcc, s74, v94
	v_mad_u64_u32 v[104:105], s[40:41], v102, s75, v[86:87]
	s_nop 0
	v_addc_co_u32_e32 v97, vcc, 0, v95, vcc
	v_mad_i32_i24 v105, v103, s75, v105
	v_add_co_u32_e32 v98, vcc, s7, v94
	v_lshl_add_u64 v[102:103], v[104:105], 0, v[76:77]
	s_nop 0
	v_addc_co_u32_e32 v99, vcc, 0, v95, vcc
	v_lshl_add_u64 v[102:103], v[102:103], 0, v[164:165]
	global_load_dwordx4 v[94:97], v[96:97], off
	s_nop 0
	global_load_dwordx4 v[98:101], v[98:99], off offset:1024
	v_add_co_u32_e32 v104, vcc, s74, v102
	v_lshl_add_u64 v[110:111], v[88:89], 0, s[46:47]
	s_nop 0
	v_addc_co_u32_e32 v105, vcc, 0, v103, vcc
	v_add_co_u32_e32 v106, vcc, s7, v102
	v_mad_u64_u32 v[112:113], s[40:41], v110, s75, v[86:87]
	s_nop 0
	v_addc_co_u32_e32 v107, vcc, 0, v103, vcc
	global_load_dwordx4 v[102:105], v[104:105], off
	s_nop 0
	global_load_dwordx4 v[106:109], v[106:107], off offset:1024
	v_mad_i32_i24 v113, v111, s75, v113
	v_lshl_add_u64 v[110:111], v[112:113], 0, v[76:77]
	v_lshl_add_u64 v[110:111], v[110:111], 0, v[164:165]
	v_lshl_add_u64 v[118:119], v[88:89], 0, s[48:49]
	v_add_co_u32_e32 v112, vcc, s74, v110
	v_mad_u64_u32 v[120:121], s[40:41], v118, s75, v[86:87]
	s_nop 0
	v_addc_co_u32_e32 v113, vcc, 0, v111, vcc
	v_mad_i32_i24 v121, v119, s75, v121
	v_add_co_u32_e32 v114, vcc, s7, v110
	v_lshl_add_u64 v[118:119], v[120:121], 0, v[76:77]
	s_nop 0
	v_addc_co_u32_e32 v115, vcc, 0, v111, vcc
	v_lshl_add_u64 v[118:119], v[118:119], 0, v[164:165]
	v_add_co_u32_e32 v120, vcc, s74, v118
	global_load_dwordx4 v[110:113], v[112:113], off
	s_nop 0
	global_load_dwordx4 v[114:117], v[114:115], off offset:1024
	v_addc_co_u32_e32 v121, vcc, 0, v119, vcc
	v_add_co_u32_e32 v122, vcc, s7, v118
	s_add_i32 s44, s24, 0x100
	s_nop 0
	v_addc_co_u32_e32 v123, vcc, 0, v119, vcc
	global_load_dwordx4 v[118:121], v[120:121], off
	s_nop 0
	global_load_dwordx4 v[122:125], v[122:123], off offset:1024
	s_mov_b32 s45, s25
	v_lshl_add_u64 v[126:127], v[88:89], 0, s[44:45]
	v_mad_u64_u32 v[128:129], s[40:41], v126, s75, v[86:87]
	v_mad_i32_i24 v129, v127, s75, v129
	v_lshl_add_u64 v[126:127], v[128:129], 0, v[76:77]
	s_add_i32 s42, s24, 0x140
	s_mov_b32 s43, s25
	v_lshl_add_u64 v[126:127], v[126:127], 0, v[164:165]
	v_lshl_add_u64 v[134:135], v[88:89], 0, s[42:43]
	v_add_co_u32_e32 v128, vcc, s74, v126
	v_mad_u64_u32 v[136:137], s[40:41], v134, s75, v[86:87]
	s_nop 0
	v_addc_co_u32_e32 v129, vcc, 0, v127, vcc
	v_mad_i32_i24 v137, v135, s75, v137
	v_add_co_u32_e32 v130, vcc, s7, v126
	v_lshl_add_u64 v[134:135], v[136:137], 0, v[76:77]
	s_nop 0
	v_addc_co_u32_e32 v131, vcc, 0, v127, vcc
	v_lshl_add_u64 v[134:135], v[134:135], 0, v[164:165]
	v_add_co_u32_e32 v136, vcc, s74, v134
	global_load_dwordx4 v[126:129], v[128:129], off
	s_nop 0
	global_load_dwordx4 v[130:133], v[130:131], off offset:1024
	v_addc_co_u32_e32 v137, vcc, 0, v135, vcc
	v_add_co_u32_e32 v138, vcc, s7, v134
	s_add_i32 s40, s24, 0x180
	s_nop 0
	v_addc_co_u32_e32 v139, vcc, 0, v135, vcc
	global_load_dwordx4 v[134:137], v[136:137], off
	s_nop 0
	global_load_dwordx4 v[138:141], v[138:139], off offset:1024
	s_mov_b32 s41, s25
	v_lshl_add_u64 v[142:143], v[88:89], 0, s[40:41]
	v_mad_u64_u32 v[144:145], s[46:47], v142, s75, v[86:87]
	v_mad_i32_i24 v145, v143, s75, v145
	v_lshl_add_u64 v[142:143], v[144:145], 0, v[76:77]
	s_addk_i32 s24, 0x1c0
	v_lshl_add_u64 v[142:143], v[142:143], 0, v[164:165]
	v_lshl_add_u64 v[88:89], v[88:89], 0, s[24:25]
	v_add_co_u32_e32 v144, vcc, s74, v142
	v_mad_u64_u32 v[166:167], s[46:47], v88, s75, v[86:87]
	s_nop 0
	v_addc_co_u32_e32 v145, vcc, 0, v143, vcc
	v_mad_i32_i24 v167, v89, s75, v167
	v_add_co_u32_e32 v160, vcc, s7, v142
	v_lshl_add_u64 v[88:89], v[166:167], 0, v[76:77]
	s_nop 0
	v_addc_co_u32_e32 v161, vcc, 0, v143, vcc
	v_lshl_add_u64 v[88:89], v[88:89], 0, v[164:165]
	v_add_co_u32_e32 v164, vcc, s74, v88
	global_load_dwordx4 v[142:145], v[144:145], off
	s_nop 0
	global_load_dwordx4 v[160:163], v[160:161], off offset:1024
	v_addc_co_u32_e32 v165, vcc, 0, v89, vcc
	v_add_co_u32_e32 v88, vcc, s7, v88
	s_mov_b32 s13, 0x10400
	s_nop 0
	v_addc_co_u32_e32 v89, vcc, 0, v89, vcc
	global_load_dwordx4 v[164:167], v[164:165], off
	s_nop 0
	global_load_dwordx4 v[168:171], v[88:89], off offset:1024
	v_add_u32_e32 v208, s44, v82
	v_mad_u64_u32 v[206:207], s[98:99], v208, s75, v[86:87]
	v_lshl_add_u64 v[206:207], v[206:207], 0, v[76:77]
	v_lshl_add_u64 v[206:207], v[206:207], 0, v[252:253]
	global_load_dwordx4 v[210:213], v[206:207], off offset:3072
	global_load_dwordx4 v[214:217], v[206:207], off offset:3136
	v_add_u32_e32 v208, s44, v84
	v_mad_u64_u32 v[206:207], s[98:99], v208, s75, v[86:87]
	v_lshl_add_u64 v[206:207], v[206:207], 0, v[76:77]
	v_lshl_add_u64 v[206:207], v[206:207], 0, v[252:253]
	global_load_dwordx4 v[218:221], v[206:207], off offset:3072
	global_load_dwordx4 v[222:225], v[206:207], off offset:3136
	v_add_u32_e32 v208, s42, v82
	v_mad_u64_u32 v[206:207], s[98:99], v208, s75, v[86:87]
	v_lshl_add_u64 v[206:207], v[206:207], 0, v[76:77]
	v_lshl_add_u64 v[206:207], v[206:207], 0, v[252:253]
	global_load_dwordx4 v[226:229], v[206:207], off offset:3072
	global_load_dwordx4 v[230:233], v[206:207], off offset:3136
	v_add_u32_e32 v208, s42, v84
	v_mad_u64_u32 v[206:207], s[98:99], v208, s75, v[86:87]
	v_lshl_add_u64 v[206:207], v[206:207], 0, v[76:77]
	v_lshl_add_u64 v[206:207], v[206:207], 0, v[252:253]
	global_load_dwordx4 v[234:237], v[206:207], off offset:3072
	s_waitcnt vmcnt(25)
; __device__ __forceinline__ void na2_task(const Params& p_, int l, int task, unsigned char* lds) {
;     ...
;       asm volatile("" ::: "memory");
; #pragma unroll
;       for (int a = 0; a < 8; ++a) { const unsigned xu[4] = {xs[a].x, xs[a].y, xs[a].z, xs[a].w}, yu[4] = {ys[a].x, ys[a].y, ys[a].z, ys[a].w};
; #pragma unroll
;           for (int i = 0; i < 4; ++i) { VTd[(chunk * 8 + 2 * i) * 260 + a * 32 + pair] = (xu[i] & 0xffffu) | (yu[i] << 16);
;               VTd[(chunk * 8 + 2 * i + 1) * 260 + a * 32 + pair] = (xu[i] >> 16) | (yu[i] & 0xffff0000u); } } }
	ds_bpermute_b32 v70, v251, v70
	ds_bpermute_b32 v71, v251, v71
	ds_bpermute_b32 v72, v251, v72
	ds_bpermute_b32 v73, v251, v73
	ds_bpermute_b32 v66, v251, v66
	ds_bpermute_b32 v67, v251, v67
	ds_bpermute_b32 v68, v251, v68
	ds_bpermute_b32 v69, v251, v69
	ds_bpermute_b32 v62, v251, v62
	ds_bpermute_b32 v63, v251, v63
	ds_bpermute_b32 v64, v251, v64
	ds_bpermute_b32 v65, v251, v65
	ds_bpermute_b32 v58, v251, v58
	ds_bpermute_b32 v59, v251, v59
	ds_bpermute_b32 v60, v251, v60
	ds_bpermute_b32 v61, v251, v61
	ds_bpermute_b32 v18, v251, v18
	ds_bpermute_b32 v19, v251, v19
	ds_bpermute_b32 v20, v251, v20
	ds_bpermute_b32 v21, v251, v21
	ds_bpermute_b32 v10, v251, v10
	ds_bpermute_b32 v11, v251, v11
	ds_bpermute_b32 v12, v251, v12
	ds_bpermute_b32 v13, v251, v13
	ds_bpermute_b32 v38, v251, v38
	ds_bpermute_b32 v39, v251, v39
	ds_bpermute_b32 v40, v251, v40
	ds_bpermute_b32 v41, v251, v41
	ds_bpermute_b32 v22, v251, v22
	ds_bpermute_b32 v23, v251, v23
	ds_bpermute_b32 v24, v251, v24
	ds_bpermute_b32 v25, v251, v25
	ds_bpermute_b32 v54, v251, v54
	ds_bpermute_b32 v55, v251, v55
	ds_bpermute_b32 v56, v251, v56
	ds_bpermute_b32 v57, v251, v57
	ds_bpermute_b32 v42, v251, v42
	ds_bpermute_b32 v43, v251, v43
	ds_bpermute_b32 v44, v251, v44
	ds_bpermute_b32 v45, v251, v45
	ds_bpermute_b32 v46, v251, v46
	ds_bpermute_b32 v47, v251, v47
	ds_bpermute_b32 v48, v251, v48
	ds_bpermute_b32 v49, v251, v49
	ds_bpermute_b32 v30, v251, v30
	ds_bpermute_b32 v31, v251, v31
	ds_bpermute_b32 v32, v251, v32
	ds_bpermute_b32 v33, v251, v33
	ds_bpermute_b32 v26, v251, v26
	ds_bpermute_b32 v27, v251, v27
	ds_bpermute_b32 v28, v251, v28
	ds_bpermute_b32 v29, v251, v29
	ds_bpermute_b32 v14, v251, v14
	ds_bpermute_b32 v15, v251, v15
	ds_bpermute_b32 v16, v251, v16
	ds_bpermute_b32 v17, v251, v17
	ds_bpermute_b32 v50, v251, v50
	ds_bpermute_b32 v51, v251, v51
	ds_bpermute_b32 v52, v251, v52
	ds_bpermute_b32 v53, v251, v53
	ds_bpermute_b32 v34, v251, v34
	ds_bpermute_b32 v35, v251, v35
	ds_bpermute_b32 v36, v251, v36
	ds_bpermute_b32 v37, v251, v37
	s_waitcnt vmcnt(7)
	v_and_b32_e32 v248, 1, v147
	v_cmp_eq_u32_e32 vcc, 1, v248
	v_and_b32_e32 v248, 2, v147
	v_cmp_eq_u32_e64 s[98:99], 2, v248
	s_nop 1
	v_cndmask_b32_e32 v246, v94, v95, vcc
	v_cndmask_b32_e32 v247, v95, v96, vcc
	v_cndmask_b32_e32 v248, v96, v97, vcc
	v_cndmask_b32_e32 v249, v97, v94, vcc
	v_cndmask_b32_e64 v94, v246, v248, s[98:99]
	v_cndmask_b32_e64 v95, v247, v249, s[98:99]
	v_cndmask_b32_e64 v96, v248, v246, s[98:99]
	v_cndmask_b32_e64 v97, v249, v247, s[98:99]
	v_cndmask_b32_e32 v246, v98, v99, vcc
	v_cndmask_b32_e32 v247, v99, v100, vcc
	v_cndmask_b32_e32 v248, v100, v101, vcc
	v_cndmask_b32_e32 v249, v101, v98, vcc
	v_cndmask_b32_e64 v98, v246, v248, s[98:99]
	v_cndmask_b32_e64 v99, v247, v249, s[98:99]
	v_cndmask_b32_e64 v100, v248, v246, s[98:99]
	v_cndmask_b32_e64 v101, v249, v247, s[98:99]
	v_cndmask_b32_e32 v246, v102, v103, vcc
	v_cndmask_b32_e32 v247, v103, v104, vcc
	v_cndmask_b32_e32 v248, v104, v105, vcc
	v_cndmask_b32_e32 v249, v105, v102, vcc
	v_cndmask_b32_e64 v102, v246, v248, s[98:99]
	v_cndmask_b32_e64 v103, v247, v249, s[98:99]
	v_cndmask_b32_e64 v104, v248, v246, s[98:99]
	v_cndmask_b32_e64 v105, v249, v247, s[98:99]
	v_cndmask_b32_e32 v246, v106, v107, vcc
	v_cndmask_b32_e32 v247, v107, v108, vcc
	v_cndmask_b32_e32 v248, v108, v109, vcc
	v_cndmask_b32_e32 v249, v109, v106, vcc
	v_cndmask_b32_e64 v106, v246, v248, s[98:99]
	v_cndmask_b32_e64 v107, v247, v249, s[98:99]
	v_cndmask_b32_e64 v108, v248, v246, s[98:99]
	v_cndmask_b32_e64 v109, v249, v247, s[98:99]
	v_cndmask_b32_e32 v246, v110, v111, vcc
	v_cndmask_b32_e32 v247, v111, v112, vcc
	v_cndmask_b32_e32 v248, v112, v113, vcc
	v_cndmask_b32_e32 v249, v113, v110, vcc
	v_cndmask_b32_e64 v110, v246, v248, s[98:99]
	v_cndmask_b32_e64 v111, v247, v249, s[98:99]
	v_cndmask_b32_e64 v112, v248, v246, s[98:99]
	v_cndmask_b32_e64 v113, v249, v247, s[98:99]
	v_cndmask_b32_e32 v246, v114, v115, vcc
	v_cndmask_b32_e32 v247, v115, v116, vcc
	v_cndmask_b32_e32 v248, v116, v117, vcc
	v_cndmask_b32_e32 v249, v117, v114, vcc
	v_cndmask_b32_e64 v114, v246, v248, s[98:99]
	v_cndmask_b32_e64 v115, v247, v249, s[98:99]
	v_cndmask_b32_e64 v116, v248, v246, s[98:99]
	v_cndmask_b32_e64 v117, v249, v247, s[98:99]
	v_cndmask_b32_e32 v246, v118, v119, vcc
	v_cndmask_b32_e32 v247, v119, v120, vcc
	v_cndmask_b32_e32 v248, v120, v121, vcc
	v_cndmask_b32_e32 v249, v121, v118, vcc
	v_cndmask_b32_e64 v118, v246, v248, s[98:99]
	v_cndmask_b32_e64 v119, v247, v249, s[98:99]
	v_cndmask_b32_e64 v120, v248, v246, s[98:99]
	v_cndmask_b32_e64 v121, v249, v247, s[98:99]
	v_cndmask_b32_e32 v246, v122, v123, vcc
	v_cndmask_b32_e32 v247, v123, v124, vcc
	v_cndmask_b32_e32 v248, v124, v125, vcc
	v_cndmask_b32_e32 v249, v125, v122, vcc
	v_cndmask_b32_e64 v122, v246, v248, s[98:99]
	v_cndmask_b32_e64 v123, v247, v249, s[98:99]
	v_cndmask_b32_e64 v124, v248, v246, s[98:99]
	v_cndmask_b32_e64 v125, v249, v247, s[98:99]
	v_cndmask_b32_e32 v246, v126, v127, vcc
	v_cndmask_b32_e32 v247, v127, v128, vcc
	v_cndmask_b32_e32 v248, v128, v129, vcc
	v_cndmask_b32_e32 v249, v129, v126, vcc
	v_cndmask_b32_e64 v126, v246, v248, s[98:99]
	v_cndmask_b32_e64 v127, v247, v249, s[98:99]
	v_cndmask_b32_e64 v128, v248, v246, s[98:99]
	v_cndmask_b32_e64 v129, v249, v247, s[98:99]
	v_cndmask_b32_e32 v246, v130, v131, vcc
	v_cndmask_b32_e32 v247, v131, v132, vcc
	v_cndmask_b32_e32 v248, v132, v133, vcc
	v_cndmask_b32_e32 v249, v133, v130, vcc
	v_cndmask_b32_e64 v130, v246, v248, s[98:99]
	v_cndmask_b32_e64 v131, v247, v249, s[98:99]
	v_cndmask_b32_e64 v132, v248, v246, s[98:99]
; __device__ __forceinline__ void na2_task(const Params& p_, int l, int task, unsigned char* lds) {
;     ...
; #pragma unroll
;       for (int a = 0; a < 8; ++a) { const unsigned xu[4] = {xs[a].x, xs[a].y, xs[a].z, xs[a].w}, yu[4] = {ys[a].x, ys[a].y, ys[a].z, ys[a].w};
; #pragma unroll
;           for (int i = 0; i < 4; ++i) { VTd[(chunk * 8 + 2 * i) * 260 + a * 32 + pair] = (xu[i] & 0xffffu) | (yu[i] << 16);
;               VTd[(chunk * 8 + 2 * i + 1) * 260 + a * 32 + pair] = (xu[i] >> 16) | (yu[i] & 0xffff0000u); } } }
	v_cndmask_b32_e64 v133, v249, v247, s[98:99]
	v_cndmask_b32_e32 v246, v134, v135, vcc
	v_cndmask_b32_e32 v247, v135, v136, vcc
	v_cndmask_b32_e32 v248, v136, v137, vcc
	v_cndmask_b32_e32 v249, v137, v134, vcc
	v_cndmask_b32_e64 v134, v246, v248, s[98:99]
	v_cndmask_b32_e64 v135, v247, v249, s[98:99]
	v_cndmask_b32_e64 v136, v248, v246, s[98:99]
	v_cndmask_b32_e64 v137, v249, v247, s[98:99]
	v_cndmask_b32_e32 v246, v138, v139, vcc
	v_cndmask_b32_e32 v247, v139, v140, vcc
	v_cndmask_b32_e32 v248, v140, v141, vcc
	v_cndmask_b32_e32 v249, v141, v138, vcc
	v_cndmask_b32_e64 v138, v246, v248, s[98:99]
	v_cndmask_b32_e64 v139, v247, v249, s[98:99]
	v_cndmask_b32_e64 v140, v248, v246, s[98:99]
	v_cndmask_b32_e64 v141, v249, v247, s[98:99]
	v_cndmask_b32_e32 v246, v142, v143, vcc
	v_cndmask_b32_e32 v247, v143, v144, vcc
	v_cndmask_b32_e32 v248, v144, v145, vcc
	v_cndmask_b32_e32 v249, v145, v142, vcc
	v_cndmask_b32_e64 v142, v246, v248, s[98:99]
	v_cndmask_b32_e64 v143, v247, v249, s[98:99]
	v_cndmask_b32_e64 v144, v248, v246, s[98:99]
	v_cndmask_b32_e64 v145, v249, v247, s[98:99]
	v_cndmask_b32_e32 v246, v160, v161, vcc
	v_cndmask_b32_e32 v247, v161, v162, vcc
	v_cndmask_b32_e32 v248, v162, v163, vcc
	v_cndmask_b32_e32 v249, v163, v160, vcc
	v_cndmask_b32_e64 v160, v246, v248, s[98:99]
	v_cndmask_b32_e64 v161, v247, v249, s[98:99]
	v_cndmask_b32_e64 v162, v248, v246, s[98:99]
	v_cndmask_b32_e64 v163, v249, v247, s[98:99]
	v_cndmask_b32_e32 v246, v164, v165, vcc
	v_cndmask_b32_e32 v247, v165, v166, vcc
	v_cndmask_b32_e32 v248, v166, v167, vcc
	v_cndmask_b32_e32 v249, v167, v164, vcc
	v_cndmask_b32_e64 v164, v246, v248, s[98:99]
	v_cndmask_b32_e64 v165, v247, v249, s[98:99]
	v_cndmask_b32_e64 v166, v248, v246, s[98:99]
	v_cndmask_b32_e64 v167, v249, v247, s[98:99]
	v_cndmask_b32_e32 v246, v168, v169, vcc
	v_cndmask_b32_e32 v247, v169, v170, vcc
	v_cndmask_b32_e32 v248, v170, v171, vcc
	v_cndmask_b32_e32 v249, v171, v168, vcc
	v_cndmask_b32_e64 v168, v246, v248, s[98:99]
	v_cndmask_b32_e64 v169, v247, v249, s[98:99]
	v_cndmask_b32_e64 v170, v248, v246, s[98:99]
	v_cndmask_b32_e64 v171, v249, v247, s[98:99]
	s_waitcnt lgkmcnt(0)
	v_lshlrev_b32_e32 v88, 2, v172
	v_mul_u32_u24_e32 v172, 0x104, v173
	v_mad_i32_i24 v81, v93, s13, 0
	v_lshlrev_b32_e32 v172, 2, v172
	v_add3_u32 v173, v81, v88, v172
	v_and_b32_e32 v248, 3, v147
	v_add_u32_e32 v249, 0, v248
	v_and_b32_e32 v249, 3, v249
	v_mul_u32_u24_e32 v249, 0x820, v249
	v_add_u32_e32 v238, v173, v249
	v_add_u32_e32 v239, 0x410, v238
	v_add_u32_e32 v249, 1, v248
	v_and_b32_e32 v249, 3, v249
	v_mul_u32_u24_e32 v249, 0x820, v249
	v_add_u32_e32 v240, v173, v249
	v_add_u32_e32 v241, 0x410, v240
	v_add_u32_e32 v249, 2, v248
	v_and_b32_e32 v249, 3, v249
	v_mul_u32_u24_e32 v249, 0x820, v249
	v_add_u32_e32 v242, v173, v249
	v_add_u32_e32 v243, 0x410, v242
	v_add_u32_e32 v249, 3, v248
	v_and_b32_e32 v249, 3, v249
	v_mul_u32_u24_e32 v249, 0x820, v249
	v_add_u32_e32 v244, v173, v249
	v_add_u32_e32 v245, 0x410, v244
	s_mov_b32 s98, 0x5040100
	s_mov_b32 s99, 0x7060302
	v_perm_b32 v246, v98, v94, s98
	v_perm_b32 v247, v106, v102, s98
	ds_write2_b32 v238, v246, v247 offset1:32
	v_perm_b32 v94, v98, v94, s99
	v_perm_b32 v102, v106, v102, s99
	ds_write2_b32 v239, v94, v102 offset1:32
	v_perm_b32 v248, v99, v95, s98
	v_perm_b32 v249, v107, v103, s98
	ds_write2_b32 v240, v248, v249 offset1:32
	v_perm_b32 v95, v99, v95, s99
	v_perm_b32 v103, v107, v103, s99
	ds_write2_b32 v241, v95, v103 offset1:32
	v_perm_b32 v246, v100, v96, s98
	v_perm_b32 v247, v108, v104, s98
	ds_write2_b32 v242, v246, v247 offset1:32
	v_perm_b32 v96, v100, v96, s99
	v_perm_b32 v104, v108, v104, s99
	ds_write2_b32 v243, v96, v104 offset1:32
	v_perm_b32 v248, v101, v97, s98
	v_perm_b32 v249, v109, v105, s98
	ds_write2_b32 v244, v248, v249 offset1:32
	v_perm_b32 v97, v101, v97, s99
	v_perm_b32 v105, v109, v105, s99
	ds_write2_b32 v245, v97, v105 offset1:32
	v_perm_b32 v246, v114, v110, s98
	v_perm_b32 v247, v122, v118, s98
	ds_write2_b32 v238, v246, v247 offset0:64 offset1:96
	v_perm_b32 v110, v114, v110, s99
	v_perm_b32 v118, v122, v118, s99
	ds_write2_b32 v239, v110, v118 offset0:64 offset1:96
	v_perm_b32 v248, v115, v111, s98
	v_perm_b32 v249, v123, v119, s98
	ds_write2_b32 v240, v248, v249 offset0:64 offset1:96
	v_perm_b32 v111, v115, v111, s99
	v_perm_b32 v119, v123, v119, s99
	ds_write2_b32 v241, v111, v119 offset0:64 offset1:96
	v_perm_b32 v246, v116, v112, s98
	v_perm_b32 v247, v124, v120, s98
	ds_write2_b32 v242, v246, v247 offset0:64 offset1:96
	v_perm_b32 v112, v116, v112, s99
	v_perm_b32 v120, v124, v120, s99
	ds_write2_b32 v243, v112, v120 offset0:64 offset1:96
	v_perm_b32 v248, v117, v113, s98
	v_perm_b32 v249, v125, v121, s98
	ds_write2_b32 v244, v248, v249 offset0:64 offset1:96
	v_perm_b32 v113, v117, v113, s99
	v_perm_b32 v121, v125, v121, s99
	ds_write2_b32 v245, v113, v121 offset0:64 offset1:96
	v_perm_b32 v246, v130, v126, s98
	v_perm_b32 v247, v138, v134, s98
	ds_write2_b32 v238, v246, v247 offset0:128 offset1:160
	v_perm_b32 v126, v130, v126, s99
	v_perm_b32 v134, v138, v134, s99
	ds_write2_b32 v239, v126, v134 offset0:128 offset1:160
	v_perm_b32 v248, v131, v127, s98
	v_perm_b32 v249, v139, v135, s98
	ds_write2_b32 v240, v248, v249 offset0:128 offset1:160
	v_perm_b32 v127, v131, v127, s99
	v_perm_b32 v135, v139, v135, s99
	ds_write2_b32 v241, v127, v135 offset0:128 offset1:160
	v_perm_b32 v246, v132, v128, s98
	v_perm_b32 v247, v140, v136, s98
	ds_write2_b32 v242, v246, v247 offset0:128 offset1:160
	v_perm_b32 v128, v132, v128, s99
	v_perm_b32 v136, v140, v136, s99
	ds_write2_b32 v243, v128, v136 offset0:128 offset1:160
; #define MFMA16(a, b, c) __builtin_amdgcn_mfma_f32_16x16x32_bf16(a, b, c, 0, 0, 0)
; __device__ __forceinline__ void na2_task(const Params& p_, int l, int task, unsigned char* lds) {
;     ...
;       for (int a = 0; a < 8; ++a) { const unsigned xu[4] = {xs[a].x, xs[a].y, xs[a].z, xs[a].w}, yu[4] = {ys[a].x, ys[a].y, ys[a].z, ys[a].w};
; #pragma unroll
;           for (int i = 0; i < 4; ++i) { VTd[(chunk * 8 + 2 * i) * 260 + a * 32 + pair] = (xu[i] & 0xffffu) | (yu[i] << 16);
;               VTd[(chunk * 8 + 2 * i + 1) * 260 + a * 32 + pair] = (xu[i] >> 16) | (yu[i] & 0xffff0000u); } } }
;     __syncthreads();
;     const int col_start = min(max(c - 8, 0), 48);
;     const float* bi = BI + hh * 465;
;     float sc[16][4]; float mx = -1e30f;
; #pragma unroll
;     for (int hf = 0; hf < 2; ++hf) {
;         if (hf == 1) {
; #pragma unroll
;             for (int i = 0; i < 8; ++i) { const int a = 4 + i / 2, ci = i % 2;
;                 const size_t ktok = (size_t)b * SEQ + (row_start + a) * 64 + kst + 16 * ci + fr;
; #pragma unroll
;                 for (int ks = 0; ks < 2; ++ks) kfr[i][ks] = *(const bf16x8v*)(Z + ktok * DIN + 3 * DG + h * 64 + 32 * ks + 8 * fq); }
;             asm volatile("" ::: "memory");
;         }
; #pragma unroll
;         for (int i = 0; i < 8; ++i) { const int a = 4 * hf + i / 2, ci = i % 2, kt = a * 2 + ci;
;             f32x4 acc = {0.f, 0.f, 0.f, 0.f};
; #pragma unroll
;             for (int ks = 0; ks < 2; ++ks) acc = MFMA16(kfr[i][ks], qf[ks], acc);
;             const int dr = row_start + a - rq;
; #pragma unroll
;             for (int r = 0; r < 4; ++r) { const int kc = kst + 16 * ci + 4 * fq + r, rel = kc - col_start, dc = kc - c;
;                 float v = acc[r] * 0.125f + bi[(dr + 7) * 31 + min(max(dc + 15, 0), 30)];
;                 v = (rel >= 0 && rel < 16) ? v : -1e30f; sc[kt][r] = v; mx = fmaxf(mx, v); } }
	v_perm_b32 v248, v133, v129, s98
	v_perm_b32 v249, v141, v137, s98
	ds_write2_b32 v244, v248, v249 offset0:128 offset1:160
	v_perm_b32 v129, v133, v129, s99
	v_perm_b32 v137, v141, v137, s99
	ds_write2_b32 v245, v129, v137 offset0:128 offset1:160
	v_perm_b32 v246, v160, v142, s98
	v_perm_b32 v247, v168, v164, s98
	ds_write2_b32 v238, v246, v247 offset0:192 offset1:224
	v_perm_b32 v142, v160, v142, s99
	v_perm_b32 v164, v168, v164, s99
	ds_write2_b32 v239, v142, v164 offset0:192 offset1:224
	v_perm_b32 v248, v161, v143, s98
	v_perm_b32 v249, v169, v165, s98
	ds_write2_b32 v240, v248, v249 offset0:192 offset1:224
	v_perm_b32 v143, v161, v143, s99
	v_perm_b32 v165, v169, v165, s99
	ds_write2_b32 v241, v143, v165 offset0:192 offset1:224
	v_perm_b32 v246, v162, v144, s98
	v_perm_b32 v247, v170, v166, s98
	ds_write2_b32 v242, v246, v247 offset0:192 offset1:224
	v_perm_b32 v144, v162, v144, s99
	v_perm_b32 v166, v170, v166, s99
	ds_write2_b32 v243, v144, v166 offset0:192 offset1:224
	v_perm_b32 v248, v163, v145, s98
	v_perm_b32 v249, v171, v167, s98
	ds_write2_b32 v244, v248, v249 offset0:192 offset1:224
	v_perm_b32 v145, v163, v145, s99
	v_perm_b32 v167, v171, v167, s99
	ds_write2_b32 v245, v145, v167 offset0:192 offset1:224
	v_mfma_f32_16x16x32_bf16 v[62:65], v[62:65], v[6:9], 0
	s_sub_i32 s9, s12, s9
	v_mfma_f32_16x16x32_bf16 v[70:73], v[70:73], v[6:9], 0
	v_lshl_add_u32 v168, v92, 2, v80
	s_mulk_i32 s9, 0x7c
	v_add_u32_e32 v169, 16, v168
	s_add_i32 s9, s9, 0
	v_sub_u32_e32 v88, v169, v91
	s_add_i32 s9, s9, 0x20800
	v_mfma_f32_16x16x32_bf16 v[58:61], v[58:61], v[2:5], v[62:65]
	v_add_u32_e32 v173, 17, v168
	v_add_u32_e32 v174, 18, v168
	v_or_b32_e32 v170, 1, v168
	v_max_i32_e32 v62, -15, v88
	v_mfma_f32_16x16x32_bf16 v[94:97], v[66:69], v[2:5], v[70:73]
	v_mov_b32_e32 v66, s9
	s_movk_i32 s9, 0x744
	v_add_u32_e32 v62, 15, v62
	v_mad_i32_i24 v98, v93, s9, v66
	v_min_u32_e32 v62, 30, v62
	v_lshl_add_u32 v103, v62, 2, v98
	v_sub_u32_e32 v62, v173, v91
	v_mfma_f32_16x16x32_bf16 v[18:21], v[18:21], v[6:9], 0
	v_max_i32_e32 v62, -15, v62
	v_add_u32_e32 v62, 15, v62
	v_min_u32_e32 v62, 30, v62
	v_lshl_add_u32 v104, v62, 2, v98
	v_mfma_f32_16x16x32_bf16 v[62:65], v[10:13], v[2:5], v[18:21]
	v_sub_u32_e32 v10, v174, v91
	v_or_b32_e32 v171, 2, v168
	v_or_b32_e32 v172, 3, v168
	v_max_i32_e32 v18, -15, v10
	v_mfma_f32_16x16x32_bf16 v[10:13], v[38:41], v[6:9], 0
	v_add_u32_e32 v175, 19, v168
	v_sub_u32_e32 v66, v168, v91
	v_sub_u32_e32 v68, v170, v91
	v_mfma_f32_16x16x32_bf16 v[38:41], v[22:25], v[2:5], v[10:13]
	v_sub_u32_e32 v70, v171, v91
	v_sub_u32_e32 v72, v172, v91
	v_sub_u32_e32 v19, v175, v91
	v_mfma_f32_16x16x32_bf16 v[10:13], v[54:57], v[6:9], 0
	v_max_i32_e32 v66, -15, v66
	v_max_i32_e32 v68, -15, v68
	v_max_i32_e32 v70, -15, v70
	v_mfma_f32_16x16x32_bf16 v[42:45], v[42:45], v[2:5], v[10:13]
	v_max_i32_e32 v72, -15, v72
	v_max_i32_e32 v19, -15, v19
	v_add_u32_e32 v66, 15, v66
	v_mfma_f32_16x16x32_bf16 v[10:13], v[46:49], v[6:9], 0
	v_add_u32_e32 v68, 15, v68
	v_add_u32_e32 v70, 15, v70
	v_add_u32_e32 v72, 15, v72
	v_mfma_f32_16x16x32_bf16 v[46:49], v[30:33], v[2:5], v[10:13]
	v_add_u32_e32 v18, 15, v18
	v_add_u32_e32 v19, 15, v19
	v_lshlrev_b32_e32 v0, 3, v92
	v_mfma_f32_16x16x32_bf16 v[10:13], v[26:29], v[6:9], 0
	v_min_u32_e32 v66, 30, v66
	v_min_u32_e32 v68, 30, v68
	v_min_u32_e32 v70, 30, v70
	v_mfma_f32_16x16x32_bf16 v[54:57], v[14:17], v[2:5], v[10:13]
	v_min_u32_e32 v72, 30, v72
	v_min_u32_e32 v18, 30, v18
	v_min_u32_e32 v19, 30, v19
	v_mfma_f32_16x16x32_bf16 v[10:13], v[50:53], v[6:9], 0
	v_lshl_add_u32 v99, v66, 2, v98
	v_lshl_add_u32 v100, v68, 2, v98
	v_lshl_add_u32 v101, v70, 2, v98
	v_mfma_f32_16x16x32_bf16 v[50:53], v[34:37], v[2:5], v[10:13]
	v_lshl_add_u32 v102, v72, 2, v98
	v_lshl_add_u32 v18, v18, 2, v98
	v_lshl_add_u32 v19, v19, 2, v98
	s_nop 0
	v_lshl_add_u64 v[10:11], v[82:83], 0, s[44:45]
	v_mad_u64_u32 v[12:13], s[12:13], v10, s75, v[86:87]
	v_mov_b32_e32 v10, v13
	v_mad_u64_u32 v[10:11], s[12:13], v11, s75, v[10:11]
	v_mov_b32_e32 v13, v10
	v_lshl_add_u64 v[10:11], v[12:13], 0, v[76:77]
	v_mov_b32_e32 v12, v252
	v_mov_b32_e32 v13, v1
	v_add_u32_e32 v176, 0x400, v99
	v_add_u32_e32 v177, 0x400, v100
	v_add_u32_e32 v197, 0x400, v101
	v_add_u32_e32 v198, 0x400, v102
	v_add_u32_e32 v199, 0x400, v103
	v_add_u32_e32 v200, 0x400, v104
	v_add_u32_e32 v201, 0x400, v18
	v_add_u32_e32 v202, 0x400, v19
	v_lshl_add_u64 v[10:11], v[10:11], 0, v[12:13]
	ds_write_b32 v204, v203
	ds_write_b32 v205, v209
	s_waitcnt lgkmcnt(0)
	s_barrier
; #define MFMA16(a, b, c) __builtin_amdgcn_mfma_f32_16x16x32_bf16(a, b, c, 0, 0, 0)
; __device__ __forceinline__ void na2_task(const Params& p_, int l, int task, unsigned char* lds) {
;     ...
;     __syncthreads();
;     const int col_start = min(max(c - 8, 0), 48);
;     const float* bi = BI + hh * 465;
;     float sc[16][4]; float mx = -1e30f;
; #pragma unroll
;     for (int hf = 0; hf < 2; ++hf) {
;         if (hf == 1) {
; #pragma unroll
;             for (int i = 0; i < 8; ++i) { const int a = 4 + i / 2, ci = i % 2;
;                 const size_t ktok = (size_t)b * SEQ + (row_start + a) * 64 + kst + 16 * ci + fr;
; #pragma unroll
;                 for (int ks = 0; ks < 2; ++ks) kfr[i][ks] = *(const bf16x8v*)(Z + ktok * DIN + 3 * DG + h * 64 + 32 * ks + 8 * fq); }
;             asm volatile("" ::: "memory");
;         }
; #pragma unroll
;         for (int i = 0; i < 8; ++i) { const int a = 4 * hf + i / 2, ci = i % 2, kt = a * 2 + ci;
;             f32x4 acc = {0.f, 0.f, 0.f, 0.f};
; #pragma unroll
;             for (int ks = 0; ks < 2; ++ks) acc = MFMA16(kfr[i][ks], qf[ks], acc);
;             const int dr = row_start + a - rq;
; #pragma unroll
;             for (int r = 0; r < 4; ++r) { const int kc = kst + 16 * ci + 4 * fq + r, rel = kc - col_start, dc = kc - c;
;                 float v = acc[r] * 0.125f + bi[(dr + 7) * 31 + min(max(dc + 15, 0), 30)];
;                 v = (rel >= 0 && rel < 16) ? v : -1e30f; sc[kt][r] = v; mx = fmaxf(mx, v); } }
	ds_read2_b32 v[66:67], v99 offset0:217 offset1:248
	ds_read2_b32 v[68:69], v100 offset0:217 offset1:248
	ds_read2_b32 v[70:71], v101 offset0:217 offset1:248
	ds_read2_b32 v[72:73], v102 offset0:217 offset1:248
	ds_read2_b32 v[88:89], v103 offset0:217 offset1:248
	ds_read2_b32 v[92:93], v104 offset0:217 offset1:248
	ds_read2_b32 v[134:135], v18 offset0:217 offset1:248
	ds_read2_b32 v[136:137], v19 offset0:217 offset1:248
	ds_read2_b32 v[138:139], v176 offset0:23 offset1:54
	ds_read2_b32 v[140:141], v177 offset0:23 offset1:54
	ds_read2_b32 v[142:143], v197 offset0:23 offset1:54
	ds_read2_b32 v[144:145], v198 offset0:23 offset1:54
	ds_read2_b32 v[160:161], v199 offset0:23 offset1:54
	ds_read2_b32 v[162:163], v200 offset0:23 offset1:54
	ds_read2_b32 v[164:165], v201 offset0:23 offset1:54
	ds_read2_b32 v[166:167], v202 offset0:23 offset1:54
	s_nop 0
	s_nop 0
	v_lshl_add_u64 v[10:11], v[84:85], 0, s[44:45]
	v_mad_u64_u32 v[14:15], s[12:13], v10, s75, v[86:87]
	v_mov_b32_e32 v10, v15
	v_mad_u64_u32 v[10:11], s[12:13], v11, s75, v[10:11]
	v_mov_b32_e32 v15, v10
	v_lshl_add_u64 v[10:11], v[14:15], 0, v[76:77]
	v_lshl_add_u64 v[10:11], v[10:11], 0, v[12:13]
	s_nop 0
	s_nop 0
	v_lshl_add_u64 v[10:11], v[82:83], 0, s[42:43]
	v_mad_u64_u32 v[14:15], s[12:13], v10, s75, v[86:87]
	v_mov_b32_e32 v10, v15
	v_mad_u64_u32 v[10:11], s[12:13], v11, s75, v[10:11]
	v_mov_b32_e32 v15, v10
	v_lshl_add_u64 v[10:11], v[14:15], 0, v[76:77]
	v_lshl_add_u64 v[10:11], v[10:11], 0, v[12:13]
	s_nop 0
	s_nop 0
	v_lshl_add_u64 v[10:11], v[84:85], 0, s[42:43]
	v_mad_u64_u32 v[14:15], s[12:13], v10, s75, v[86:87]
	v_mov_b32_e32 v10, v15
	v_mad_u64_u32 v[10:11], s[12:13], v11, s75, v[10:11]
	v_mov_b32_e32 v15, v10
	v_lshl_add_u64 v[10:11], v[14:15], 0, v[76:77]
	v_lshl_add_u64 v[10:11], v[10:11], 0, v[12:13]
	s_nop 0
	global_load_dwordx4 v[126:129], v[10:11], off offset:3136
	v_lshl_add_u64 v[10:11], v[82:83], 0, s[40:41]
	v_mad_u64_u32 v[14:15], s[12:13], v10, s75, v[86:87]
	v_mov_b32_e32 v10, v15
	v_mad_u64_u32 v[10:11], s[12:13], v11, s75, v[10:11]
	v_mov_b32_e32 v15, v10
	v_lshl_add_u64 v[10:11], v[14:15], 0, v[76:77]
	v_lshl_add_u64 v[10:11], v[10:11], 0, v[12:13]
	global_load_dwordx4 v[130:133], v[10:11], off offset:3072
	global_load_dwordx4 v[34:37], v[10:11], off offset:3136
	v_lshl_add_u64 v[10:11], v[84:85], 0, s[40:41]
	v_mad_u64_u32 v[14:15], s[12:13], v10, s75, v[86:87]
	v_mov_b32_e32 v10, v15
	v_mad_u64_u32 v[10:11], s[12:13], v11, s75, v[10:11]
	v_mov_b32_e32 v15, v10
	v_lshl_add_u64 v[10:11], v[14:15], 0, v[76:77]
	v_lshl_add_u64 v[10:11], v[10:11], 0, v[12:13]
	global_load_dwordx4 v[30:33], v[10:11], off offset:3072
	global_load_dwordx4 v[26:29], v[10:11], off offset:3136
	v_lshl_add_u64 v[10:11], v[82:83], 0, s[24:25]
	v_mad_u64_u32 v[14:15], s[12:13], v10, s75, v[86:87]
	v_mov_b32_e32 v10, v15
	v_mad_u64_u32 v[10:11], s[12:13], v11, s75, v[10:11]
	v_mov_b32_e32 v15, v10
	v_lshl_add_u64 v[10:11], v[14:15], 0, v[76:77]
	v_lshl_add_u64 v[10:11], v[10:11], 0, v[12:13]
	global_load_dwordx4 v[22:25], v[10:11], off offset:3072
	global_load_dwordx4 v[18:21], v[10:11], off offset:3136
	v_lshl_add_u64 v[10:11], v[84:85], 0, s[24:25]
	v_mad_u64_u32 v[14:15], s[12:13], v10, s75, v[86:87]
	v_mov_b32_e32 v10, v15
	v_mad_u64_u32 v[10:11], s[12:13], v11, s75, v[10:11]
	v_mov_b32_e32 v15, v10
	v_sub_u32_e64 v82, v91, 8 clamp
	v_lshl_add_u64 v[10:11], v[14:15], 0, v[76:77]
	v_min_u32_e32 v82, 48, v82
	v_lshl_add_u64 v[10:11], v[10:11], 0, v[12:13]
	v_sub_u32_e32 v84, v171, v82
	global_load_dwordx4 v[14:17], v[10:11], off offset:3072
	s_nop 0
	global_load_dwordx4 v[10:13], v[10:11], off offset:3136
	v_cmp_gt_u32_e64 s[46:47], 16, v84
	v_sub_u32_e32 v84, v172, v82
	v_sub_u32_e32 v83, v168, v82
	v_cmp_gt_u32_e64 s[42:43], 16, v84
	v_sub_u32_e32 v84, v169, v82
	v_cmp_gt_u32_e32 vcc, 16, v83
	v_sub_u32_e32 v83, v170, v82
	s_waitcnt lgkmcnt(11)
	v_fmamk_f32 v58, v58, 0x3e000000, v88
	v_cmp_gt_u32_e64 s[44:45], 16, v84
	v_fmamk_f32 v66, v94, 0x3e000000, v66
	v_fmamk_f32 v68, v95, 0x3e000000, v68
	v_cmp_gt_u32_e64 s[40:41], 16, v83
	v_cndmask_b32_e64 v84, v194, v58, s[44:45]
	v_sub_u32_e32 v58, v173, v82
	v_cndmask_b32_e32 v66, v194, v66, vcc
	v_cndmask_b32_e64 v68, v194, v68, s[40:41]
	s_mov_b32 s9, 0xf149f2ca
	v_fmamk_f32 v70, v96, 0x3e000000, v70
	v_fmamk_f32 v72, v97, 0x3e000000, v72
	s_waitcnt lgkmcnt(10)
	v_fmamk_f32 v59, v59, 0x3e000000, v92
	v_cmp_gt_u32_e64 s[48:49], 16, v58
	v_max3_f32 v83, v66, s9, v68
	v_cndmask_b32_e64 v70, v194, v70, s[46:47]
	v_cndmask_b32_e64 v72, v194, v72, s[42:43]
	v_cndmask_b32_e64 v85, v194, v59, s[48:49]
	v_sub_u32_e32 v59, v174, v82
	v_max3_f32 v83, v83, v70, v72
	s_waitcnt lgkmcnt(9)
	v_fmamk_f32 v60, v60, 0x3e000000, v134
	v_cmp_gt_u32_e64 s[50:51], 16, v59
	v_sub_u32_e32 v59, v175, v82
	v_max3_f32 v58, v83, v84, v85
	v_cndmask_b32_e64 v83, v194, v60, s[50:51]
	s_waitcnt lgkmcnt(8)
	v_fmamk_f32 v60, v61, 0x3e000000, v136
	v_cmp_gt_u32_e64 s[52:53], 16, v59
	v_fmac_f32_e32 v67, 0x3e000000, v62
	v_fmac_f32_e32 v69, 0x3e000000, v63
	v_cndmask_b32_e64 v82, v194, v60, s[52:53]
	v_fmac_f32_e32 v93, 0x3e000000, v39
	s_waitcnt lgkmcnt(7)
	v_fmamk_f32 v39, v42, 0x3e000000, v138
	v_max3_f32 v58, v58, v83, v82
	v_cndmask_b32_e32 v62, v194, v67, vcc
	v_cndmask_b32_e64 v63, v194, v69, s[40:41]
	v_fmac_f32_e32 v71, 0x3e000000, v64
	v_fmac_f32_e32 v73, 0x3e000000, v65
	v_fmac_f32_e32 v89, 0x3e000000, v38
	v_cndmask_b32_e32 v88, v194, v39, vcc
	s_waitcnt lgkmcnt(6)
	v_fmamk_f32 v39, v43, 0x3e000000, v140
	v_max3_f32 v58, v58, v62, v63
	v_cndmask_b32_e64 v67, v194, v71, s[46:47]
	v_cndmask_b32_e64 v69, v194, v73, s[42:43]
	v_cndmask_b32_e64 v71, v194, v89, s[44:45]
	v_cndmask_b32_e64 v89, v194, v39, s[40:41]
	s_waitcnt lgkmcnt(5)
; #define MFMA16(a, b, c) __builtin_amdgcn_mfma_f32_16x16x32_bf16(a, b, c, 0, 0, 0)
; __device__ __forceinline__ void na2_task(const Params& p_, int l, int task, unsigned char* lds) {
;     ...
;             for (int i = 0; i < 8; ++i) { const int a = 4 + i / 2, ci = i % 2;
;                 const size_t ktok = (size_t)b * SEQ + (row_start + a) * 64 + kst + 16 * ci + fr;
; #pragma unroll
;                 for (int ks = 0; ks < 2; ++ks) kfr[i][ks] = *(const bf16x8v*)(Z + ktok * DIN + 3 * DG + h * 64 + 32 * ks + 8 * fq); }
;             asm volatile("" ::: "memory");
;         }
; #pragma unroll
;         for (int i = 0; i < 8; ++i) { const int a = 4 * hf + i / 2, ci = i % 2, kt = a * 2 + ci;
;             f32x4 acc = {0.f, 0.f, 0.f, 0.f};
; #pragma unroll
;             for (int ks = 0; ks < 2; ++ks) acc = MFMA16(kfr[i][ks], qf[ks], acc);
;             const int dr = row_start + a - rq;
; #pragma unroll
;             for (int r = 0; r < 4; ++r) { const int kc = kst + 16 * ci + 4 * fq + r, rel = kc - col_start, dc = kc - c;
;                 float v = acc[r] * 0.125f + bi[(dr + 7) * 31 + min(max(dc + 15, 0), 30)];
;                 v = (rel >= 0 && rel < 16) ? v : -1e30f; sc[kt][r] = v; mx = fmaxf(mx, v); } }
	v_fmamk_f32 v39, v44, 0x3e000000, v142
	v_max3_f32 v58, v58, v67, v69
	v_cndmask_b32_e64 v73, v194, v93, s[48:49]
	v_fmac_f32_e32 v135, 0x3e000000, v40
	v_fmac_f32_e32 v137, 0x3e000000, v41
	v_cndmask_b32_e64 v91, v194, v39, s[46:47]
	s_waitcnt lgkmcnt(4)
	v_fmamk_f32 v39, v45, 0x3e000000, v144
	v_max3_f32 v38, v58, v71, v73
	v_cndmask_b32_e64 v86, v194, v135, s[50:51]
	v_cndmask_b32_e64 v87, v194, v137, s[52:53]
	v_cndmask_b32_e64 v92, v194, v39, s[42:43]
	s_waitcnt lgkmcnt(3)
	v_fmamk_f32 v39, v46, 0x3e000000, v160
	v_max3_f32 v38, v38, v86, v87
	v_cndmask_b32_e64 v93, v194, v39, s[44:45]
	s_waitcnt lgkmcnt(2)
	v_fmamk_f32 v39, v47, 0x3e000000, v162
	v_max3_f32 v38, v38, v88, v89
	v_cndmask_b32_e64 v94, v194, v39, s[48:49]
	s_waitcnt lgkmcnt(1)
	v_fmamk_f32 v39, v48, 0x3e000000, v164
	v_max3_f32 v38, v38, v91, v92
	v_cndmask_b32_e64 v95, v194, v39, s[50:51]
	s_waitcnt lgkmcnt(0)
	v_fmamk_f32 v39, v49, 0x3e000000, v166
	v_max3_f32 v38, v38, v93, v94
	v_cndmask_b32_e64 v96, v194, v39, s[52:53]
	v_fmac_f32_e32 v139, 0x3e000000, v54
	v_fmac_f32_e32 v141, 0x3e000000, v55
	v_max3_f32 v38, v38, v95, v96
	v_cndmask_b32_e32 v97, v194, v139, vcc
	v_cndmask_b32_e64 v134, v194, v141, s[40:41]
	v_fmac_f32_e32 v143, 0x3e000000, v56
	v_fmac_f32_e32 v145, 0x3e000000, v57
	v_max3_f32 v38, v38, v97, v134
	v_cndmask_b32_e64 v135, v194, v143, s[46:47]
	v_cndmask_b32_e64 v136, v194, v145, s[42:43]
	v_fmac_f32_e32 v161, 0x3e000000, v50
	v_fmac_f32_e32 v163, 0x3e000000, v51
	v_max3_f32 v38, v38, v135, v136
	v_cndmask_b32_e64 v137, v194, v161, s[44:45]
	v_cndmask_b32_e64 v138, v194, v163, s[48:49]
	v_max3_f32 v42, v38, v137, v138
	s_waitcnt vmcnt(0)
	ds_bpermute_b32 v98, v251, v210
	ds_bpermute_b32 v99, v251, v211
	ds_bpermute_b32 v100, v251, v212
	ds_bpermute_b32 v101, v251, v213
	ds_bpermute_b32 v102, v251, v214
	ds_bpermute_b32 v103, v251, v215
	ds_bpermute_b32 v104, v251, v216
	ds_bpermute_b32 v105, v251, v217
	ds_bpermute_b32 v106, v251, v218
	ds_bpermute_b32 v107, v251, v219
	ds_bpermute_b32 v108, v251, v220
	ds_bpermute_b32 v109, v251, v221
	ds_bpermute_b32 v110, v251, v222
	ds_bpermute_b32 v111, v251, v223
	ds_bpermute_b32 v112, v251, v224
	ds_bpermute_b32 v113, v251, v225
	ds_bpermute_b32 v114, v251, v226
	ds_bpermute_b32 v115, v251, v227
	ds_bpermute_b32 v116, v251, v228
	ds_bpermute_b32 v117, v251, v229
	ds_bpermute_b32 v118, v251, v230
	ds_bpermute_b32 v119, v251, v231
	ds_bpermute_b32 v120, v251, v232
	ds_bpermute_b32 v121, v251, v233
	ds_bpermute_b32 v122, v251, v234
	ds_bpermute_b32 v123, v251, v235
	ds_bpermute_b32 v124, v251, v236
	ds_bpermute_b32 v125, v251, v237
	ds_bpermute_b32 v126, v251, v126
	ds_bpermute_b32 v127, v251, v127
	ds_bpermute_b32 v128, v251, v128
	ds_bpermute_b32 v129, v251, v129
	ds_bpermute_b32 v130, v251, v130
	ds_bpermute_b32 v131, v251, v131
	ds_bpermute_b32 v132, v251, v132
	ds_bpermute_b32 v133, v251, v133
	ds_bpermute_b32 v34, v251, v34
	ds_bpermute_b32 v35, v251, v35
	ds_bpermute_b32 v36, v251, v36
	ds_bpermute_b32 v37, v251, v37
	ds_bpermute_b32 v30, v251, v30
	ds_bpermute_b32 v31, v251, v31
	ds_bpermute_b32 v32, v251, v32
	ds_bpermute_b32 v33, v251, v33
	ds_bpermute_b32 v26, v251, v26
	ds_bpermute_b32 v27, v251, v27
	ds_bpermute_b32 v28, v251, v28
	ds_bpermute_b32 v29, v251, v29
	ds_bpermute_b32 v22, v251, v22
	ds_bpermute_b32 v23, v251, v23
	ds_bpermute_b32 v24, v251, v24
	ds_bpermute_b32 v25, v251, v25
	ds_bpermute_b32 v18, v251, v18
	ds_bpermute_b32 v19, v251, v19
	ds_bpermute_b32 v20, v251, v20
	ds_bpermute_b32 v21, v251, v21
	ds_bpermute_b32 v14, v251, v14
	ds_bpermute_b32 v15, v251, v15
	ds_bpermute_b32 v16, v251, v16
	ds_bpermute_b32 v17, v251, v17
	ds_bpermute_b32 v10, v251, v10
	ds_bpermute_b32 v11, v251, v11
	ds_bpermute_b32 v12, v251, v12
	ds_bpermute_b32 v13, v251, v13
	s_waitcnt lgkmcnt(0)
	v_mfma_f32_16x16x32_bf16 v[38:41], v[98:101], v[6:9], 0
	ds_read2_b32 v[46:47], v176 offset0:85 offset1:116
	ds_read2_b32 v[48:49], v177 offset0:85 offset1:116
	ds_read2_b32 v[50:51], v197 offset0:85 offset1:116
	s_waitcnt vmcnt(14)
	v_mfma_f32_16x16x32_bf16 v[38:41], v[102:105], v[2:5], v[38:41]
	v_fmac_f32_e32 v165, 0x3e000000, v52
	v_fmac_f32_e32 v167, 0x3e000000, v53
	ds_read2_b32 v[52:53], v198 offset0:85 offset1:116
	ds_read2_b32 v[54:55], v199 offset0:85 offset1:116
	ds_read2_b32 v[56:57], v200 offset0:85 offset1:116
	s_waitcnt lgkmcnt(5)
	s_nop 1
	v_fmamk_f32 v38, v38, 0x3e000000, v46
	v_cndmask_b32_e32 v98, v194, v38, vcc
	s_waitcnt lgkmcnt(4)
	v_fmamk_f32 v38, v39, 0x3e000000, v48
	v_cndmask_b32_e64 v48, v194, v38, s[40:41]
	s_waitcnt lgkmcnt(3)
	v_fmamk_f32 v38, v40, 0x3e000000, v50
	v_cndmask_b32_e64 v50, v194, v38, s[46:47]
	s_waitcnt lgkmcnt(2)
	v_fmamk_f32 v38, v41, 0x3e000000, v52
	v_cndmask_b32_e64 v52, v194, v38, s[42:43]
	s_waitcnt vmcnt(13)
	v_mfma_f32_16x16x32_bf16 v[38:41], v[106:109], v[6:9], 0
	v_cndmask_b32_e64 v139, v194, v165, s[50:51]
	v_cndmask_b32_e64 v140, v194, v167, s[52:53]
	ds_read2_b32 v[58:59], v201 offset0:85 offset1:116
	s_waitcnt vmcnt(12)
	v_mfma_f32_16x16x32_bf16 v[38:41], v[110:113], v[2:5], v[38:41]
	v_max3_f32 v42, v42, v139, v140
	ds_read2_b32 v[60:61], v202 offset0:85 offset1:116
	v_max3_f32 v42, v42, v98, v48
	v_max3_f32 v42, v42, v50, v52
	s_waitcnt vmcnt(5)
	v_mfma_f32_16x16x32_bf16 v[30:33], v[30:33], v[6:9], 0
	s_waitcnt lgkmcnt(3)
	s_nop 0
	v_fmamk_f32 v38, v38, 0x3e000000, v54
	v_cndmask_b32_e64 v54, v194, v38, s[44:45]
	s_waitcnt lgkmcnt(2)
	v_fmamk_f32 v38, v39, 0x3e000000, v56
	v_cndmask_b32_e64 v99, v194, v38, s[48:49]
	v_max3_f32 v38, v42, v54, v99
	v_mfma_f32_16x16x32_bf16 v[42:45], v[114:117], v[6:9], 0
	s_waitcnt lgkmcnt(1)
; #define MFMA16(a, b, c) __builtin_amdgcn_mfma_f32_16x16x32_bf16(a, b, c, 0, 0, 0)
; __device__ __forceinline__ void na2_task(const Params& p_, int l, int task, unsigned char* lds) {
;     ...
; #pragma unroll
;         for (int i = 0; i < 8; ++i) { const int a = 4 * hf + i / 2, ci = i % 2, kt = a * 2 + ci;
;             f32x4 acc = {0.f, 0.f, 0.f, 0.f};
; #pragma unroll
;             for (int ks = 0; ks < 2; ++ks) acc = MFMA16(kfr[i][ks], qf[ks], acc);
;             const int dr = row_start + a - rq;
; #pragma unroll
;             for (int r = 0; r < 4; ++r) { const int kc = kst + 16 * ci + 4 * fq + r, rel = kc - col_start, dc = kc - c;
;                 float v = acc[r] * 0.125f + bi[(dr + 7) * 31 + min(max(dc + 15, 0), 30)];
;                 v = (rel >= 0 && rel < 16) ? v : -1e30f; sc[kt][r] = v; mx = fmaxf(mx, v); } }
;     }
;     mx = fmaxf(mx, __shfl_xor(mx, 16)); mx = fmaxf(mx, __shfl_xor(mx, 32));
	v_fmamk_f32 v39, v40, 0x3e000000, v58
	v_cndmask_b32_e64 v100, v194, v39, s[50:51]
	s_waitcnt lgkmcnt(0)
	v_fmamk_f32 v39, v41, 0x3e000000, v60
	v_cndmask_b32_e64 v101, v194, v39, s[52:53]
	v_max3_f32 v46, v38, v100, v101
	v_mfma_f32_16x16x32_bf16 v[38:41], v[118:121], v[2:5], v[42:45]
	v_lshl_add_u64 v[78:79], v[78:79], 0, v[0:1]
	s_mov_b32 s9, 0x12d20000
	v_mfma_f32_16x16x32_bf16 v[42:45], v[122:125], v[6:9], 0
	s_waitcnt vmcnt(4)
	v_mfma_f32_16x16x32_bf16 v[26:29], v[26:29], v[2:5], v[30:33]
	s_nop 2
	v_fmac_f32_e32 v47, 0x3e000000, v38
	v_fmac_f32_e32 v49, 0x3e000000, v39
	v_cndmask_b32_e32 v102, v194, v47, vcc
	v_cndmask_b32_e64 v49, v194, v49, s[40:41]
	v_fmac_f32_e32 v51, 0x3e000000, v40
	v_fmac_f32_e32 v53, 0x3e000000, v41
	v_max3_f32 v38, v46, v102, v49
	v_cndmask_b32_e64 v51, v194, v51, s[46:47]
	v_cndmask_b32_e64 v53, v194, v53, s[42:43]
	v_max3_f32 v46, v38, v51, v53
	v_mfma_f32_16x16x32_bf16 v[38:41], v[126:129], v[2:5], v[42:45]
	s_waitcnt vmcnt(3)
	v_mfma_f32_16x16x32_bf16 v[22:25], v[22:25], v[6:9], 0
	s_waitcnt vmcnt(2)
	v_mfma_f32_16x16x32_bf16 v[18:21], v[18:21], v[2:5], v[22:25]
	s_nop 3
	v_fmac_f32_e32 v55, 0x3e000000, v38
	v_fmac_f32_e32 v57, 0x3e000000, v39
	v_fmac_f32_e32 v59, 0x3e000000, v40
	v_fmac_f32_e32 v61, 0x3e000000, v41
	v_mfma_f32_16x16x32_bf16 v[38:41], v[130:133], v[6:9], 0
	v_cndmask_b32_e64 v55, v194, v55, s[44:45]
	v_cndmask_b32_e64 v103, v194, v57, s[48:49]
	v_max3_f32 v42, v46, v55, v103
	v_cndmask_b32_e64 v104, v194, v59, s[50:51]
	v_cndmask_b32_e64 v105, v194, v61, s[52:53]
	v_max3_f32 v46, v42, v104, v105
	ds_read2_b32 v[42:43], v176 offset0:147 offset1:178
	ds_read2_b32 v[44:45], v177 offset0:147 offset1:178
	v_mfma_f32_16x16x32_bf16 v[34:37], v[34:37], v[2:5], v[38:41]
	s_waitcnt lgkmcnt(1)
	v_fmac_f32_e32 v43, 0x3e000000, v18
	s_nop 0
	ds_read2_b32 v[38:39], v197 offset0:147 offset1:178
	s_waitcnt vmcnt(1)
	v_mfma_f32_16x16x32_bf16 v[6:9], v[14:17], v[6:9], 0
	s_nop 1
	v_fmamk_f32 v34, v34, 0x3e000000, v42
	v_cndmask_b32_e32 v42, v194, v34, vcc
	s_waitcnt lgkmcnt(1)
	v_fmamk_f32 v40, v35, 0x3e000000, v44
	ds_read2_b32 v[34:35], v198 offset0:147 offset1:178
	v_cndmask_b32_e64 v44, v194, v40, s[40:41]
	s_waitcnt lgkmcnt(1)
	v_fmamk_f32 v36, v36, 0x3e000000, v38
	v_max3_f32 v40, v46, v42, v44
	v_cndmask_b32_e64 v38, v194, v36, s[46:47]
	s_waitcnt lgkmcnt(0)
	v_fmamk_f32 v34, v37, 0x3e000000, v34
	v_cndmask_b32_e64 v34, v194, v34, s[42:43]
	v_max3_f32 v46, v40, v38, v34
	ds_read2_b32 v[36:37], v199 offset0:147 offset1:178
	ds_read2_b32 v[40:41], v200 offset0:147 offset1:178
	ds_read2_b32 v[30:31], v201 offset0:147 offset1:178
	s_waitcnt vmcnt(0)
	v_mfma_f32_16x16x32_bf16 v[2:5], v[10:13], v[2:5], v[6:9]
	v_fmac_f32_e32 v45, 0x3e000000, v19
	s_waitcnt lgkmcnt(2)
	v_fmamk_f32 v26, v26, 0x3e000000, v36
	v_cndmask_b32_e64 v36, v194, v26, s[44:45]
	s_waitcnt lgkmcnt(1)
	v_fmamk_f32 v26, v27, 0x3e000000, v40
	v_cndmask_b32_e64 v40, v194, v26, s[48:49]
	ds_read2_b32 v[26:27], v202 offset0:147 offset1:178
	s_waitcnt lgkmcnt(1)
	v_fmamk_f32 v28, v28, 0x3e000000, v30
	v_max3_f32 v32, v46, v36, v40
	v_cndmask_b32_e64 v106, v194, v28, s[50:51]
	v_cndmask_b32_e32 v43, v194, v43, vcc
	s_waitcnt lgkmcnt(0)
	v_fmamk_f32 v26, v29, 0x3e000000, v26
	v_cndmask_b32_e64 v107, v194, v26, s[52:53]
	v_max3_f32 v26, v32, v106, v107
	v_cndmask_b32_e64 v45, v194, v45, s[40:41]
	v_fmac_f32_e32 v39, 0x3e000000, v20
	v_fmac_f32_e32 v35, 0x3e000000, v21
	v_fmac_f32_e32 v31, 0x3e000000, v4
	v_and_b32_e32 v4, 64, v178
	v_max3_f32 v18, v26, v43, v45
	v_cndmask_b32_e64 v39, v194, v39, s[46:47]
	v_cndmask_b32_e64 v108, v194, v35, s[42:43]
	v_fmac_f32_e32 v37, 0x3e000000, v2
	v_fmac_f32_e32 v41, 0x3e000000, v3
	v_xor_b32_e32 v3, 16, v178
	v_add_u32_e32 v4, 64, v4
	v_max3_f32 v14, v18, v39, v108
	v_cndmask_b32_e64 v109, v194, v37, s[44:45]
	v_cndmask_b32_e64 v41, v194, v41, s[48:49]
	v_fmac_f32_e32 v27, 0x3e000000, v5
	v_cmp_lt_i32_e32 vcc, v3, v4
	v_max3_f32 v2, v14, v109, v41
	v_cndmask_b32_e64 v110, v194, v31, s[50:51]
	v_cndmask_b32_e64 v111, v194, v27, s[52:53]
	v_cndmask_b32_e32 v3, v178, v3, vcc
	v_max3_f32 v2, v2, v110, v111
	v_lshlrev_b32_e32 v112, 2, v3
	ds_bpermute_b32 v3, v112, v2
	s_waitcnt lgkmcnt(0)
	v_max_f32_e32 v3, v3, v3
	v_max_f32_e32 v2, v2, v3
	v_xor_b32_e32 v3, 32, v178
	v_cmp_lt_i32_e32 vcc, v3, v4
	s_nop 1
	v_cndmask_b32_e32 v3, v178, v3, vcc
	v_lshlrev_b32_e32 v113, 2, v3
	ds_bpermute_b32 v3, v113, v2
	s_waitcnt lgkmcnt(0)
; __device__ __forceinline__ unsigned pk2(float lo, float hi) { return f2bf(lo) | (f2bf(hi) << 16); }
; __device__ __forceinline__ void na2_task(const Params& p_, int l, int task, unsigned char* lds) {
;     ...
;     float sum = 0.f; unsigned pp[16][2];
; #pragma unroll
;     for (int kt = 0; kt < 16; ++kt) { const float e0 = __expf(sc[kt][0] - mx), e1 = __expf(sc[kt][1] - mx), e2 = __expf(sc[kt][2] - mx), e3 = __expf(sc[kt][3] - mx);
;         sum += (e0 + e1) + (e2 + e3); pp[kt][0] = pk2(e0, e1); pp[kt][1] = pk2(e2, e3); }
;     sum += __shfl_xor(sum, 16); sum += __shfl_xor(sum, 32);
	v_max_f32_e32 v3, v3, v3
	v_max_f32_e32 v114, v2, v3
	v_sub_f32_e32 v6, v84, v114
	v_mul_f32_e32 v6, 0x3fb8aa3b, v6
	v_sub_f32_e32 v3, v68, v114
	v_exp_f32_e32 v60, v6
	v_sub_f32_e32 v6, v85, v114
	v_mul_f32_e32 v3, 0x3fb8aa3b, v3
	v_mul_f32_e32 v6, 0x3fb8aa3b, v6
	v_sub_f32_e32 v2, v66, v114
	v_exp_f32_e32 v4, v3
	v_sub_f32_e32 v3, v70, v114
	v_sub_f32_e32 v5, v72, v114
	v_exp_f32_e32 v64, v6
	v_sub_f32_e32 v6, v83, v114
	v_mul_f32_e32 v2, 0x3fb8aa3b, v2
	v_mul_f32_e32 v3, 0x3fb8aa3b, v3
	v_mul_f32_e32 v5, 0x3fb8aa3b, v5
	v_mul_f32_e32 v6, 0x3fb8aa3b, v6
	v_exp_f32_e32 v2, v2
	v_exp_f32_e32 v3, v3
	v_exp_f32_e32 v5, v5
	v_exp_f32_e32 v61, v6
	v_sub_f32_e32 v6, v82, v114
	v_mul_f32_e32 v6, 0x3fb8aa3b, v6
	v_exp_f32_e32 v65, v6
	v_pk_add_f32 v[6:7], v[2:3], v[4:5]
	v_sub_f32_e32 v8, v87, v114
	v_add_f32_e32 v6, v6, v7
	v_add_f32_e32 v9, 0, v6
	v_pk_add_f32 v[6:7], v[60:61], v[64:65]
	v_mul_f32_e32 v8, 0x3fb8aa3b, v8
	v_pk_add_f32 v[6:7], v[6:7], v[6:7] op_sel_hi:[0,1]
	v_sub_f32_e32 v6, v62, v114
	v_mul_f32_e32 v6, 0x3fb8aa3b, v6
	v_exp_f32_e32 v84, v6
	v_sub_f32_e32 v6, v63, v114
	v_mul_f32_e32 v6, 0x3fb8aa3b, v6
	v_exp_f32_e32 v85, v6
	v_sub_f32_e32 v6, v67, v114
	v_mul_f32_e32 v6, 0x3fb8aa3b, v6
	v_exp_f32_e32 v115, v6
	v_sub_f32_e32 v6, v69, v114
	v_mul_f32_e32 v6, 0x3fb8aa3b, v6
	v_exp_f32_e32 v116, v6
	v_sub_f32_e32 v6, v71, v114
	v_mul_f32_e32 v6, 0x3fb8aa3b, v6
	v_exp_f32_e32 v12, v6
	v_sub_f32_e32 v6, v73, v114
	v_mul_f32_e32 v6, 0x3fb8aa3b, v6
	v_exp_f32_e32 v62, v6
	v_sub_f32_e32 v6, v86, v114
	v_mul_f32_e32 v6, 0x3fb8aa3b, v6
	v_exp_f32_e32 v6, v6
	v_exp_f32_e32 v8, v8
	v_add_f32_e32 v13, v84, v85
	v_add_f32_e32 v63, v115, v116
	v_pk_add_f32 v[10:11], v[12:13], v[62:63]
	v_pk_add_f32 v[14:15], v[6:7], v[8:9]
	v_sub_f32_e32 v7, v88, v114
	v_pk_add_f32 v[10:11], v[10:11], v[14:15]
	v_mul_f32_e32 v7, 0x3fb8aa3b, v7
	v_pk_add_f32 v[14:15], v[10:11], v[10:11] op_sel_hi:[0,1]
	v_exp_f32_e32 v10, v7
	v_sub_f32_e32 v7, v89, v114
	v_mul_f32_e32 v7, 0x3fb8aa3b, v7
	v_exp_f32_e32 v58, v7
	v_sub_f32_e32 v7, v91, v114
	v_mul_f32_e32 v7, 0x3fb8aa3b, v7
	v_exp_f32_e32 v11, v7
	v_sub_f32_e32 v7, v92, v114
	v_mul_f32_e32 v7, 0x3fb8aa3b, v7
	v_exp_f32_e32 v59, v7
	v_sub_f32_e32 v7, v93, v114
	v_mul_f32_e32 v7, 0x3fb8aa3b, v7
	v_exp_f32_e32 v13, v7
	v_sub_f32_e32 v7, v94, v114
	v_mul_f32_e32 v7, 0x3fb8aa3b, v7
	v_exp_f32_e32 v86, v7
	v_sub_f32_e32 v7, v95, v114
	v_mul_f32_e32 v7, 0x3fb8aa3b, v7
	v_exp_f32_e32 v87, v7
	v_sub_f32_e32 v7, v96, v114
	v_mul_f32_e32 v7, 0x3fb8aa3b, v7
	v_exp_f32_e32 v88, v7
	v_sub_f32_e32 v7, v97, v114
	v_pk_add_f32 v[16:17], v[10:11], v[58:59]
	v_mul_f32_e32 v7, 0x3fb8aa3b, v7
	v_pk_add_f32 v[18:19], v[16:17], v[16:17] op_sel_hi:[0,1]
	v_exp_f32_e32 v16, v7
	v_sub_f32_e32 v7, v134, v114
	v_mul_f32_e32 v7, 0x3fb8aa3b, v7
	v_exp_f32_e32 v20, v7
	v_sub_f32_e32 v7, v135, v114
	v_mul_f32_e32 v7, 0x3fb8aa3b, v7
	v_exp_f32_e32 v18, v7
	v_sub_f32_e32 v7, v136, v114
	v_mul_f32_e32 v7, 0x3fb8aa3b, v7
	v_exp_f32_e32 v14, v7
	v_sub_f32_e32 v7, v137, v114
	v_mul_f32_e32 v7, 0x3fb8aa3b, v7
	v_exp_f32_e32 v68, v7
	v_sub_f32_e32 v7, v138, v114
	v_mul_f32_e32 v7, 0x3fb8aa3b, v7
	v_exp_f32_e32 v72, v7
	v_sub_f32_e32 v7, v139, v114
	v_mul_f32_e32 v7, 0x3fb8aa3b, v7
	v_exp_f32_e32 v69, v7
	v_sub_f32_e32 v7, v140, v114
	v_mul_f32_e32 v7, 0x3fb8aa3b, v7
	v_exp_f32_e32 v73, v7
	v_sub_f32_e32 v7, v98, v114
	v_mul_f32_e32 v7, 0x3fb8aa3b, v7
	v_pk_add_f32 v[24:25], v[18:19], v[14:15]
	v_exp_f32_e32 v19, v7
	v_sub_f32_e32 v7, v48, v114
	v_add_f32_e32 v17, v13, v86
	v_add_f32_e32 v21, v87, v88
	v_mul_f32_e32 v7, 0x3fb8aa3b, v7
	v_pk_add_f32 v[22:23], v[16:17], v[20:21]
	v_exp_f32_e32 v21, v7
	v_sub_f32_e32 v7, v50, v114
	v_mul_f32_e32 v7, 0x3fb8aa3b, v7
	v_exp_f32_e32 v89, v7
	v_sub_f32_e32 v7, v52, v114
	v_mul_f32_e32 v7, 0x3fb8aa3b, v7
	v_exp_f32_e32 v91, v7
	v_sub_f32_e32 v7, v54, v114
	v_mul_f32_e32 v7, 0x3fb8aa3b, v7
	v_exp_f32_e32 v66, v7
	v_sub_f32_e32 v7, v99, v114
	v_pk_add_f32 v[22:23], v[22:23], v[24:25]
	v_mul_f32_e32 v7, 0x3fb8aa3b, v7
	v_pk_add_f32 v[56:57], v[22:23], v[22:23] op_sel_hi:[0,1]
	v_pk_add_f32 v[22:23], v[68:69], v[72:73]
	v_exp_f32_e32 v70, v7
	v_sub_f32_e32 v7, v100, v114
	v_pk_add_f32 v[46:47], v[22:23], v[22:23] op_sel_hi:[0,1]
	v_mul_f32_e32 v7, 0x3fb8aa3b, v7
	v_exp_f32_e32 v46, v7
	v_sub_f32_e32 v7, v101, v114
	v_mul_f32_e32 v7, 0x3fb8aa3b, v7
	v_exp_f32_e32 v56, v7
	v_add_f32_e32 v67, v19, v21
	v_add_f32_e32 v71, v89, v91
	v_pk_add_f32 v[22:23], v[66:67], v[70:71]
	v_pk_add_f32 v[24:25], v[46:47], v[56:57]
	v_sub_f32_e32 v7, v102, v114
	v_pk_add_f32 v[22:23], v[22:23], v[24:25]
	v_mul_f32_e32 v7, 0x3fb8aa3b, v7
	v_pk_add_f32 v[26:27], v[22:23], v[22:23] op_sel_hi:[0,1]
	v_exp_f32_e32 v22, v7
	v_sub_f32_e32 v7, v49, v114
	v_mul_f32_e32 v7, 0x3fb8aa3b, v7
	v_exp_f32_e32 v24, v7
	v_sub_f32_e32 v7, v51, v114
	v_mul_f32_e32 v7, 0x3fb8aa3b, v7
	v_exp_f32_e32 v23, v7
	v_sub_f32_e32 v7, v53, v114
	v_mul_f32_e32 v7, 0x3fb8aa3b, v7
	v_exp_f32_e32 v25, v7
	v_sub_f32_e32 v7, v55, v114
	v_mul_f32_e32 v7, 0x3fb8aa3b, v7
	v_exp_f32_e32 v67, v7
	v_sub_f32_e32 v7, v103, v114
	v_mul_f32_e32 v7, 0x3fb8aa3b, v7
	v_exp_f32_e32 v71, v7
	v_sub_f32_e32 v7, v104, v114
	v_mul_f32_e32 v7, 0x3fb8aa3b, v7
	v_exp_f32_e32 v92, v7
	v_sub_f32_e32 v7, v105, v114
	v_mul_f32_e32 v7, 0x3fb8aa3b, v7
	v_exp_f32_e32 v93, v7
	v_sub_f32_e32 v7, v42, v114
	v_pk_add_f32 v[28:29], v[22:23], v[24:25]
	v_mul_f32_e32 v7, 0x3fb8aa3b, v7
	v_pk_add_f32 v[30:31], v[28:29], v[28:29] op_sel_hi:[0,1]
	v_exp_f32_e32 v28, v7
	v_sub_f32_e32 v7, v44, v114
	v_mul_f32_e32 v7, 0x3fb8aa3b, v7
	v_exp_f32_e32 v32, v7
	v_sub_f32_e32 v7, v38, v114
	v_mul_f32_e32 v7, 0x3fb8aa3b, v7
; __device__ __forceinline__ unsigned pk2(float lo, float hi) { return f2bf(lo) | (f2bf(hi) << 16); }
; #define MFMA16(a, b, c) __builtin_amdgcn_mfma_f32_16x16x32_bf16(a, b, c, 0, 0, 0)
; __device__ __forceinline__ void na2_task(const Params& p_, int l, int task, unsigned char* lds) {
;     ...
;     float sum = 0.f; unsigned pp[16][2];
; #pragma unroll
;     for (int kt = 0; kt < 16; ++kt) { const float e0 = __expf(sc[kt][0] - mx), e1 = __expf(sc[kt][1] - mx), e2 = __expf(sc[kt][2] - mx), e3 = __expf(sc[kt][3] - mx);
;         sum += (e0 + e1) + (e2 + e3); pp[kt][0] = pk2(e0, e1); pp[kt][1] = pk2(e2, e3); }
;     sum += __shfl_xor(sum, 16); sum += __shfl_xor(sum, 32);
;     const float inv = 1.f / sum;
;     const bf16* VTh = VT + (size_t)hh * 64 * 520;
; #pragma unroll
;     for (int dt = 0; dt < 4; ++dt) { f32x4 o = {0.f, 0.f, 0.f, 0.f};
; #pragma unroll
;         for (int t = 0; t < 8; ++t) { const int k0 = 2 * t, k1 = 2 * t + 1, a0 = k0 / 2, c0 = k0 % 2, a1 = k1 / 2, c1 = k1 % 2;
;             const u32x2 vlo = *(const u32x2*)(VTh + (16 * dt + fr) * 520 + a0 * 64 + kst + 16 * c0 + 4 * fq), vhi = *(const u32x2*)(VTh + (16 * dt + fr) * 520 + a1 * 64 + kst + 16 * c1 + 4 * fq);
;             o = MFMA16(mk8(vlo.x, vlo.y, vhi.x, vhi.y), mk8(pp[k0][0], pp[k0][1], pp[k1][0], pp[k1][1]), o); }
	v_exp_f32_e32 v30, v7
	v_sub_f32_e32 v7, v34, v114
	v_mul_f32_e32 v7, 0x3fb8aa3b, v7
	v_exp_f32_e32 v26, v7
	v_sub_f32_e32 v7, v36, v114
	v_mul_f32_e32 v7, 0x3fb8aa3b, v7
	v_exp_f32_e32 v48, v7
	v_sub_f32_e32 v7, v40, v114
	v_mul_f32_e32 v7, 0x3fb8aa3b, v7
	v_exp_f32_e32 v52, v7
	v_sub_f32_e32 v7, v106, v114
	v_mul_f32_e32 v7, 0x3fb8aa3b, v7
	v_exp_f32_e32 v49, v7
	v_sub_f32_e32 v7, v107, v114
	v_mul_f32_e32 v7, 0x3fb8aa3b, v7
	v_exp_f32_e32 v53, v7
	v_sub_f32_e32 v7, v43, v114
	v_mul_f32_e32 v7, 0x3fb8aa3b, v7
	v_pk_add_f32 v[36:37], v[30:31], v[26:27]
	v_exp_f32_e32 v31, v7
	v_sub_f32_e32 v7, v45, v114
	v_add_f32_e32 v29, v67, v71
	v_add_f32_e32 v33, v92, v93
	v_mul_f32_e32 v7, 0x3fb8aa3b, v7
	v_pk_add_f32 v[34:35], v[28:29], v[32:33]
	v_exp_f32_e32 v33, v7
	v_sub_f32_e32 v7, v39, v114
	v_mul_f32_e32 v7, 0x3fb8aa3b, v7
	v_exp_f32_e32 v94, v7
	v_sub_f32_e32 v7, v108, v114
	v_mul_f32_e32 v7, 0x3fb8aa3b, v7
	v_exp_f32_e32 v95, v7
	v_sub_f32_e32 v7, v109, v114
	v_mul_f32_e32 v7, 0x3fb8aa3b, v7
	v_exp_f32_e32 v50, v7
	v_sub_f32_e32 v7, v41, v114
	v_pk_add_f32 v[34:35], v[34:35], v[36:37]
	v_mul_f32_e32 v7, 0x3fb8aa3b, v7
	v_pk_add_f32 v[36:37], v[34:35], v[34:35] op_sel_hi:[0,1]
	v_pk_add_f32 v[34:35], v[48:49], v[52:53]
	v_exp_f32_e32 v54, v7
	v_sub_f32_e32 v7, v110, v114
	v_pk_add_f32 v[34:35], v[34:35], v[34:35] op_sel_hi:[0,1]
	v_mul_f32_e32 v7, 0x3fb8aa3b, v7
	v_exp_f32_e32 v34, v7
	v_sub_f32_e32 v7, v111, v114
	v_mul_f32_e32 v7, 0x3fb8aa3b, v7
	v_exp_f32_e32 v36, v7
	v_add_f32_e32 v51, v31, v33
	v_add_f32_e32 v55, v94, v95
	v_pk_add_f32 v[38:39], v[50:51], v[54:55]
	v_pk_add_f32 v[40:41], v[34:35], v[36:37]
	v_pk_add_f32 v[38:39], v[38:39], v[40:41]
	v_add_f32_e32 v7, v38, v39
	ds_bpermute_b32 v9, v112, v7
	v_lshlrev_b64 v[38:39], 12, v[74:75]
	v_lshl_add_u64 v[38:39], s[62:63], 0, v[38:39]
	v_lshl_add_u64 v[38:39], v[38:39], 0, v[76:77]
	v_lshl_add_u64 v[42:43], v[38:39], 0, v[0:1]
	s_waitcnt lgkmcnt(0)
	v_add_f32_e32 v7, v7, v9
	ds_bpermute_b32 v9, v113, v7
	s_waitcnt lgkmcnt(0)
	v_add_f32_e32 v7, v7, v9
	v_div_scale_f32 v9, s[12:13], v7, v7, 1.0
	v_rcp_f32_e32 v15, v9
	s_mov_b64 s[12:13], 0x1400
	v_fma_f32 v17, -v9, v15, 1.0
	v_fmac_f32_e32 v15, v17, v15
	v_div_scale_f32 v17, vcc, 1.0, v7, 1.0
	v_mul_f32_e32 v27, v17, v15
	v_fma_f32 v29, -v9, v27, v17
	v_fmac_f32_e32 v27, v29, v15
	v_fma_f32 v9, -v9, v27, v17
	v_div_fmas_f32 v9, v9, v15, v27
	v_div_fixup_f32 v40, v9, v7, 1.0
	v_lshl_add_u32 v7, v80, 1, v81
	v_mul_u32_u24_e32 v9, 0x410, v90
	v_add3_u32 v0, v7, v9, v0
	v_bfe_u32 v15, v5, 16, 1
	v_bfe_u32 v17, v4, 16, 1
	v_cvt_pk_bf16_f32 v207, v60, v64
	v_cvt_pk_bf16_f32 v206, v61, v65
	v_add3_u32 v17, v4, v17, s14
	v_add3_u32 v15, v5, v15, s14
	v_bfe_u32 v7, v2, 16, 1
	v_bfe_u32 v9, v3, 16, 1
	v_add3_u32 v3, v3, v9, s14
	v_add3_u32 v2, v2, v7, s14
	v_mov_b32_e32 v5, v206
	v_mov_b32_e32 v4, v207
	v_bfe_u32 v7, v8, 16, 1
	v_cvt_pk_bf16_f32 v208, v12, v62
	v_lshrrev_b32_e32 v3, 16, v3
	v_add3_u32 v7, v8, v7, s14
	v_bfe_u32 v9, v6, 16, 1
	v_and_or_b32 v3, v15, s15, v3
	v_cvt_pk_bf16_f32 v209, v115, v116
	v_add3_u32 v6, v6, v9, s14
	v_lshrrev_b32_e32 v6, 16, v6
	v_and_or_b32 v9, v7, s15, v6
	v_mov_b32_e32 v8, v208
	v_mov_b32_e32 v7, v209
	v_cvt_pk_bf16_f32 v210, v87, v88
	v_cvt_pk_bf16_f32 v211, v13, v86
	v_mov_b32_e32 v13, v210
	v_mov_b32_e32 v12, v211
	v_cvt_pk_bf16_f32 v212, v18, v14
	v_cvt_pk_bf16_f32 v213, v16, v20
	v_mov_b32_e32 v15, v212
	v_mov_b32_e32 v14, v213
	v_bfe_u32 v29, v21, 16, 1
	v_add3_u32 v29, v21, v29, s14
	v_bfe_u32 v21, v46, 16, 1
	v_add3_u32 v21, v46, v21, s14
	v_add_co_u32_e32 v46, vcc, s74, v78
	ds_read2_b64 v[74:77], v0 offset1:4
	s_nop 0
	v_addc_co_u32_e32 v47, vcc, 0, v79, vcc
	global_load_dwordx2 v[46:47], v[46:47], off offset:1024
	ds_read2_b64 v[80:83], v0 offset0:16 offset1:20
	v_lshrrev_b32_e32 v2, 16, v2
	v_and_or_b32 v2, v17, s15, v2
	v_cvt_pk_bf16_f32 v214, v84, v85
	s_waitcnt lgkmcnt(1)
	v_mfma_f32_16x16x32_bf16 v[74:77], v[74:77], v[2:5], 0
	v_mov_b32_e32 v6, v214
	v_cvt_pk_bf16_f32 v215, v11, v59
	s_waitcnt lgkmcnt(0)
	v_mfma_f32_16x16x32_bf16 v[60:63], v[80:83], v[6:9], v[74:77]
	v_cvt_pk_bf16_f32 v216, v10, v58
	ds_read2_b64 v[74:77], v0 offset0:32 offset1:36
	v_mov_b32_e32 v11, v215
	v_mov_b32_e32 v10, v216
	v_cvt_pk_bf16_f32 v217, v69, v73
	s_waitcnt lgkmcnt(0)
	v_mfma_f32_16x16x32_bf16 v[58:61], v[74:77], v[10:13], v[60:63]
	v_cvt_pk_bf16_f32 v218, v68, v72
	s_nop 0
	ds_read2_b64 v[62:65], v0 offset0:48 offset1:52
	v_mov_b32_e32 v17, v217
	v_mov_b32_e32 v16, v218
	v_bfe_u32 v35, v19, 16, 1
	s_waitcnt lgkmcnt(0)
	v_mfma_f32_16x16x32_bf16 v[58:61], v[62:65], v[14:17], v[58:61]
	ds_read2_b64 v[62:65], v0 offset0:64 offset1:68
	v_bfe_u32 v18, v56, 16, 1
	v_cvt_pk_bf16_f32 v219, v66, v70
	v_cvt_pk_bf16_f32 v220, v89, v91
	v_add3_u32 v19, v19, v35, s14
	v_add3_u32 v18, v56, v18, s14
	v_lshrrev_b32_e32 v21, 16, v21
	v_lshrrev_b32_e32 v35, 16, v19
	v_and_or_b32 v21, v18, s15, v21
	v_mov_b32_e32 v20, v219
	v_mov_b32_e32 v19, v220
	v_and_or_b32 v18, v29, s15, v35
	v_cvt_pk_bf16_f32 v221, v92, v93
	s_waitcnt lgkmcnt(0)
	v_mfma_f32_16x16x32_bf16 v[56:59], v[62:65], v[18:21], v[58:61]
	v_bfe_u32 v35, v25, 16, 1
	v_bfe_u32 v37, v24, 16, 1
	v_add3_u32 v37, v24, v37, s14
	ds_read2_b64 v[60:63], v0 offset0:80 offset1:84
	v_add3_u32 v35, v25, v35, s14
	v_bfe_u32 v27, v22, 16, 1
	v_bfe_u32 v29, v23, 16, 1
	v_cvt_pk_bf16_f32 v222, v67, v71
	v_add3_u32 v23, v23, v29, s14
	v_add3_u32 v22, v22, v27, s14
	v_lshrrev_b32_e32 v22, 16, v22
	v_lshrrev_b32_e32 v23, 16, v23
	v_mov_b32_e32 v25, v221
	v_mov_b32_e32 v24, v222
	v_and_or_b32 v23, v35, s15, v23
	v_and_or_b32 v22, v37, s15, v22
	s_waitcnt lgkmcnt(0)
; __device__ __forceinline__ unsigned pk2(float lo, float hi) { return f2bf(lo) | (f2bf(hi) << 16); }
; __device__ __forceinline__ float bflo(unsigned u) { return __uint_as_float(u << 16); }
; __device__ __forceinline__ float bfhi(unsigned u) { return __uint_as_float(u & 0xffff0000u); }
; __device__ __forceinline__ float silu_f(float v) { return v / (1.f + __expf(-v)); }
; #define MFMA16(a, b, c) __builtin_amdgcn_mfma_f32_16x16x32_bf16(a, b, c, 0, 0, 0)
; __device__ __forceinline__ void na2_task(const Params& p_, int l, int task, unsigned char* lds) {
;     ...
;     for (int dt = 0; dt < 4; ++dt) { f32x4 o = {0.f, 0.f, 0.f, 0.f};
; #pragma unroll
;         for (int t = 0; t < 8; ++t) { const int k0 = 2 * t, k1 = 2 * t + 1, a0 = k0 / 2, c0 = k0 % 2, a1 = k1 / 2, c1 = k1 % 2;
;             const u32x2 vlo = *(const u32x2*)(VTh + (16 * dt + fr) * 520 + a0 * 64 + kst + 16 * c0 + 4 * fq), vhi = *(const u32x2*)(VTh + (16 * dt + fr) * 520 + a1 * 64 + kst + 16 * c1 + 4 * fq);
;             o = MFMA16(mk8(vlo.x, vlo.y, vhi.x, vhi.y), mk8(pp[k0][0], pp[k0][1], pp[k1][0], pp[k1][1]), o); }
;         const u32x2 gz = *(const u32x2*)(Z + qtok * DIN + 5 * DG + h * 64 + 16 * dt + 4 * fq); u32x2 ov;
;         ov.x = pk2(o[0] * inv * silu_f(bflo(gz.x)), o[1] * inv * silu_f(bfhi(gz.x))); ov.y = pk2(o[2] * inv * silu_f(bflo(gz.y)), o[3] * inv * silu_f(bfhi(gz.y)));
;         *(u32x2*)(CAT + qtok * DM + 512 + h * 64 + 16 * dt + 4 * fq) = ov; }
	v_mfma_f32_16x16x32_bf16 v[56:59], v[60:63], v[22:25], v[56:59]
	ds_read2_b64 v[60:63], v0 offset0:96 offset1:100
	v_cvt_pk_bf16_f32 v223, v30, v26
	v_cvt_pk_bf16_f32 v226, v28, v32
	v_cvt_pk_bf16_f32 v224, v49, v53
	v_cvt_pk_bf16_f32 v225, v48, v52
	v_mov_b32_e32 v27, v223
	v_mov_b32_e32 v29, v224
	v_mov_b32_e32 v28, v225
	v_mov_b32_e32 v26, v226
	v_bfe_u32 v30, v36, 16, 1
	v_bfe_u32 v37, v33, 16, 1
	s_waitcnt lgkmcnt(0)
	v_mfma_f32_16x16x32_bf16 v[56:59], v[60:63], v[26:29], v[56:59]
	ds_read2_b64 v[60:63], v0 offset0:112 offset1:116
	v_add3_u32 v30, v36, v30, s14
	v_add3_u32 v36, v33, v37, s14
	v_bfe_u32 v33, v34, 16, 1
	v_bfe_u32 v37, v31, 16, 1
	v_cvt_pk_bf16_f32 v227, v50, v54
	v_cvt_pk_bf16_f32 v228, v94, v95
	v_add3_u32 v33, v34, v33, s14
	v_add3_u32 v31, v31, v37, s14
	v_lshrrev_b32_e32 v33, 16, v33
	v_lshrrev_b32_e32 v37, 16, v31
	v_and_or_b32 v33, v30, s15, v33
	v_mov_b32_e32 v32, v227
	v_mov_b32_e32 v31, v228
	v_and_or_b32 v30, v36, s15, v37
	s_waitcnt vmcnt(0)
	v_lshlrev_b32_e32 v41, 16, v47
	v_lshl_add_u64 v[44:45], v[78:79], 0, s[12:13]
	s_waitcnt lgkmcnt(0)
	v_mfma_f32_16x16x32_bf16 v[34:37], v[60:63], v[30:33], v[56:59]
	global_load_dwordx2 v[48:49], v[44:45], off offset:32
	global_load_dwordx2 v[50:51], v[44:45], off offset:64
	s_nop 0
	global_load_dwordx2 v[44:45], v[44:45], off offset:96
	v_lshlrev_b32_e32 v56, 16, v46
	v_mul_f32_e32 v52, 0xbfb8aa3b, v56
	v_and_b32_e32 v57, 0xffff0000, v47
	v_mul_f32_e32 v47, 0xbfb8aa3b, v41
	v_exp_f32_e32 v52, v52
	v_exp_f32_e32 v53, v47
	s_mov_b64 s[12:13], 0x12d20400
	v_lshl_add_u64 v[38:39], v[42:43], 0, s[12:13]
	v_mov_b32_e32 v54, v34
	v_pk_add_f32 v[52:53], v[52:53], 1.0 op_sel_hi:[1,0]
	v_mov_b32_e32 v55, v36
	v_div_scale_f32 v47, s[12:13], v53, v53, v41
	v_rcp_f32_e32 v59, v47
	v_and_b32_e32 v58, 0xffff0000, v46
	v_pk_mul_f32 v[54:55], v[40:41], v[54:55] op_sel_hi:[0,1]
	v_mul_f32_e32 v46, 0xbfb8aa3b, v58
	v_fma_f32 v34, -v47, v59, 1.0
	v_fmac_f32_e32 v59, v34, v59
	v_div_scale_f32 v34, vcc, v41, v53, v41
	v_mul_f32_e32 v36, v34, v59
	v_fma_f32 v60, -v47, v36, v34
	v_fmac_f32_e32 v36, v60, v59
	v_fma_f32 v34, -v47, v36, v34
	v_div_scale_f32 v47, s[12:13], v52, v52, v56
	v_rcp_f32_e32 v60, v47
	v_div_fmas_f32 v34, v34, v59, v36
	v_div_fixup_f32 v53, v34, v53, v41
	v_exp_f32_e32 v46, v46
	v_fma_f32 v34, -v47, v60, 1.0
	v_fmac_f32_e32 v60, v34, v60
	v_div_scale_f32 v34, vcc, v56, v52, v56
	v_mul_f32_e32 v36, v34, v60
	v_fma_f32 v41, -v47, v36, v34
	v_fmac_f32_e32 v36, v41, v60
	v_mul_f32_e32 v41, 0xbfb8aa3b, v57
	v_fma_f32 v34, -v47, v36, v34
	v_exp_f32_e32 v47, v41
	v_div_fmas_f32 v34, v34, v60, v36
	v_div_fixup_f32 v52, v34, v52, v56
	v_mov_b32_e32 v36, v35
	v_pk_add_f32 v[46:47], v[46:47], 1.0 op_sel_hi:[1,0]
	v_pk_mul_f32 v[64:65], v[54:55], v[52:53]
	v_div_scale_f32 v34, s[12:13], v47, v47, v57
	v_rcp_f32_e32 v41, v34
	v_div_scale_f32 v52, s[12:13], v46, v46, v58
	v_rcp_f32_e32 v56, v52
	v_fma_f32 v35, -v34, v41, 1.0
	v_pk_mul_f32 v[60:61], v[40:41], v[36:37] op_sel_hi:[0,1]
	v_fmac_f32_e32 v41, v35, v41
	v_div_scale_f32 v35, vcc, v57, v47, v57
	v_mul_f32_e32 v36, v35, v41
	v_fma_f32 v37, -v34, v36, v35
	v_fmac_f32_e32 v36, v37, v41
	v_fma_f32 v34, -v34, v36, v35
	v_div_fmas_f32 v34, v34, v41, v36
	v_div_fixup_f32 v47, v34, v47, v57
	v_fma_f32 v34, -v52, v56, 1.0
	v_add_u32_e32 v66, 0x4000, v0
	v_fmac_f32_e32 v56, v34, v56
	v_div_scale_f32 v41, vcc, v58, v46, v58
	ds_read2_b64 v[34:37], v66 offset0:32 offset1:36
	v_mul_f32_e32 v57, v41, v56
	v_fma_f32 v53, -v52, v57, v41
	v_fmac_f32_e32 v57, v53, v56
	v_fma_f32 v41, -v52, v57, v41
	ds_read2_b64 v[52:55], v66 offset0:48 offset1:52
	v_div_fmas_f32 v41, v41, v56, v57
	v_div_fixup_f32 v46, v41, v46, v58
	ds_read2_b64 v[56:59], v66 offset0:64 offset1:68
	s_waitcnt lgkmcnt(2)
	v_mfma_f32_16x16x32_bf16 v[34:37], v[34:37], v[2:5], 0
	v_mul_f32_e64 v46, v60, v46
	v_mul_f32_e64 v47, v61, v47
	ds_read2_b64 v[60:63], v66 offset0:80 offset1:84
	v_and_b32_sdwa v41, v65, v179 dst_sel:DWORD dst_unused:UNUSED_PAD src0_sel:WORD_1 src1_sel:DWORD
	s_waitcnt lgkmcnt(2)
	v_mfma_f32_16x16x32_bf16 v[34:37], v[52:55], v[6:9], v[34:37]
	v_and_b32_sdwa v52, v64, v179 dst_sel:DWORD dst_unused:UNUSED_PAD src0_sel:WORD_1 src1_sel:DWORD
	v_add3_u32 v64, v64, v52, s14
	ds_read2_b64 v[52:55], v66 offset0:96 offset1:100
	s_waitcnt lgkmcnt(2)
	v_mfma_f32_16x16x32_bf16 v[34:37], v[56:59], v[10:13], v[34:37]
	ds_read2_b64 v[56:59], v66 offset0:112 offset1:116
	v_add3_u32 v41, v65, v41, s14
	v_and_b32_sdwa v65, v47, v179 dst_sel:DWORD dst_unused:UNUSED_PAD src0_sel:WORD_1 src1_sel:DWORD
	s_waitcnt lgkmcnt(2)
	v_mfma_f32_16x16x32_bf16 v[34:37], v[60:63], v[14:17], v[34:37]
	ds_read2_b64 v[60:63], v66 offset0:128 offset1:132
	v_and_b32_sdwa v67, v46, v179 dst_sel:DWORD dst_unused:UNUSED_PAD src0_sel:WORD_1 src1_sel:DWORD
	v_add3_u32 v47, v47, v65, s14
	s_waitcnt lgkmcnt(2)
	v_mfma_f32_16x16x32_bf16 v[34:37], v[52:55], v[18:21], v[34:37]
	ds_read2_b64 v[52:55], v66 offset0:144 offset1:148
	v_add3_u32 v46, v46, v67, s14
	v_and_b32_e32 v47, 0xffff0000, v47
	s_waitcnt lgkmcnt(2)
	v_mfma_f32_16x16x32_bf16 v[34:37], v[56:59], v[22:25], v[34:37]
	v_and_b32_e32 v46, 0xffff0000, v46
	v_add_co_u32_e32 v42, vcc, s9, v42
	s_waitcnt lgkmcnt(1)
	v_mfma_f32_16x16x32_bf16 v[34:37], v[60:63], v[26:29], v[34:37]
	v_or_b32_sdwa v47, v47, v41 dst_sel:DWORD dst_unused:UNUSED_PAD src0_sel:DWORD src1_sel:WORD_1
	v_or_b32_sdwa v46, v46, v64 dst_sel:DWORD dst_unused:UNUSED_PAD src0_sel:DWORD src1_sel:WORD_1
	v_addc_co_u32_e32 v43, vcc, 0, v43, vcc
	s_waitcnt lgkmcnt(0)
	v_mfma_f32_16x16x32_bf16 v[34:37], v[52:55], v[30:33], v[34:37]
	s_waitcnt vmcnt(2)
; __device__ __forceinline__ unsigned pk2(float lo, float hi) { return f2bf(lo) | (f2bf(hi) << 16); }
; __device__ __forceinline__ float bflo(unsigned u) { return __uint_as_float(u << 16); }
; __device__ __forceinline__ float bfhi(unsigned u) { return __uint_as_float(u & 0xffff0000u); }
; __device__ __forceinline__ float silu_f(float v) { return v / (1.f + __expf(-v)); }
; #define MFMA16(a, b, c) __builtin_amdgcn_mfma_f32_16x16x32_bf16(a, b, c, 0, 0, 0)
; __device__ __forceinline__ void na2_task(const Params& p_, int l, int task, unsigned char* lds) {
;     ...
;     for (int dt = 0; dt < 4; ++dt) { f32x4 o = {0.f, 0.f, 0.f, 0.f};
; #pragma unroll
;         for (int t = 0; t < 8; ++t) { const int k0 = 2 * t, k1 = 2 * t + 1, a0 = k0 / 2, c0 = k0 % 2, a1 = k1 / 2, c1 = k1 % 2;
;             const u32x2 vlo = *(const u32x2*)(VTh + (16 * dt + fr) * 520 + a0 * 64 + kst + 16 * c0 + 4 * fq), vhi = *(const u32x2*)(VTh + (16 * dt + fr) * 520 + a1 * 64 + kst + 16 * c1 + 4 * fq);
;             o = MFMA16(mk8(vlo.x, vlo.y, vhi.x, vhi.y), mk8(pp[k0][0], pp[k0][1], pp[k1][0], pp[k1][1]), o); }
;         const u32x2 gz = *(const u32x2*)(Z + qtok * DIN + 5 * DG + h * 64 + 16 * dt + 4 * fq); u32x2 ov;
;         ov.x = pk2(o[0] * inv * silu_f(bflo(gz.x)), o[1] * inv * silu_f(bfhi(gz.x))); ov.y = pk2(o[2] * inv * silu_f(bflo(gz.y)), o[3] * inv * silu_f(bfhi(gz.y)));
;         *(u32x2*)(CAT + qtok * DM + 512 + h * 64 + 16 * dt + 4 * fq) = ov; }
	v_lshlrev_b32_e32 v41, 16, v49
	v_lshlrev_b32_e32 v52, 16, v48
	global_store_dwordx2 v[42:43], v[46:47], off offset:1024
	v_mul_f32_e32 v42, 0xbfb8aa3b, v52
	v_mul_f32_e32 v43, 0xbfb8aa3b, v41
	v_exp_f32_e32 v42, v42
	v_exp_f32_e32 v43, v43
	v_and_b32_e32 v58, 0xffff0000, v48
	v_mov_b32_e32 v48, v34
	v_and_b32_e32 v53, 0xffff0000, v49
	v_pk_add_f32 v[42:43], v[42:43], 1.0 op_sel_hi:[1,0]
	v_mov_b32_e32 v49, v36
	v_div_scale_f32 v47, s[12:13], v43, v43, v41
	v_rcp_f32_e32 v54, v47
	v_pk_mul_f32 v[48:49], v[40:41], v[48:49] op_sel_hi:[0,1]
	v_mul_f32_e32 v46, 0xbfb8aa3b, v58
	v_exp_f32_e32 v46, v46
	v_fma_f32 v34, -v47, v54, 1.0
	v_fmac_f32_e32 v54, v34, v54
	v_div_scale_f32 v34, vcc, v41, v43, v41
	v_mul_f32_e32 v36, v34, v54
	v_fma_f32 v55, -v47, v36, v34
	v_fmac_f32_e32 v36, v55, v54
	v_fma_f32 v34, -v47, v36, v34
	v_div_scale_f32 v47, s[12:13], v42, v42, v52
	v_rcp_f32_e32 v55, v47
	v_div_fmas_f32 v34, v34, v54, v36
	v_div_fixup_f32 v43, v34, v43, v41
	v_add_u32_e32 v64, 0x8000, v0
	v_fma_f32 v34, -v47, v55, 1.0
	v_fmac_f32_e32 v55, v34, v55
	v_div_scale_f32 v34, vcc, v52, v42, v52
	v_mul_f32_e32 v36, v34, v55
	v_fma_f32 v41, -v47, v36, v34
	v_fmac_f32_e32 v36, v41, v55
	v_mul_f32_e32 v41, 0xbfb8aa3b, v53
	v_fma_f32 v34, -v47, v36, v34
	v_exp_f32_e32 v47, v41
	v_div_fmas_f32 v34, v34, v55, v36
	v_div_fixup_f32 v42, v34, v42, v52
	v_mov_b32_e32 v36, v35
	v_pk_add_f32 v[56:57], v[46:47], 1.0 op_sel_hi:[1,0]
	v_pk_mul_f32 v[42:43], v[48:49], v[42:43]
	v_div_scale_f32 v34, s[12:13], v57, v57, v53
	v_rcp_f32_e32 v41, v34
	v_div_scale_f32 v52, s[12:13], v56, v56, v58
	v_rcp_f32_e32 v59, v52
	v_fma_f32 v35, -v34, v41, 1.0
	v_pk_mul_f32 v[60:61], v[40:41], v[36:37] op_sel_hi:[0,1]
	v_fmac_f32_e32 v41, v35, v41
	v_div_scale_f32 v35, vcc, v53, v57, v53
	v_mul_f32_e32 v36, v35, v41
	v_fma_f32 v37, -v34, v36, v35
	v_fmac_f32_e32 v36, v37, v41
	v_fma_f32 v34, -v34, v36, v35
	v_div_fmas_f32 v34, v34, v41, v36
	v_div_fixup_f32 v63, v34, v57, v53
	ds_read2_b64 v[34:37], v64 offset0:64 offset1:68
	v_fma_f32 v41, -v52, v59, 1.0
	v_fmac_f32_e32 v59, v41, v59
	v_div_scale_f32 v41, vcc, v58, v56, v58
	ds_read2_b64 v[46:49], v64 offset0:80 offset1:84
	v_mul_f32_e32 v57, v41, v59
	v_fma_f32 v53, -v52, v57, v41
	v_fmac_f32_e32 v57, v53, v59
	v_fma_f32 v41, -v52, v57, v41
	ds_read2_b64 v[52:55], v64 offset0:96 offset1:100
	s_waitcnt lgkmcnt(2)
	v_mfma_f32_16x16x32_bf16 v[34:37], v[34:37], v[2:5], 0
	v_div_fmas_f32 v41, v41, v59, v57
	v_div_fixup_f32 v62, v41, v56, v58
	ds_read2_b64 v[56:59], v64 offset0:112 offset1:116
	s_waitcnt lgkmcnt(2)
	v_mfma_f32_16x16x32_bf16 v[34:37], v[46:49], v[6:9], v[34:37]
	ds_read2_b64 v[46:49], v64 offset0:128 offset1:132
	v_pk_mul_f32 v[60:61], v[60:61], v[62:63]
	v_and_b32_sdwa v41, v43, v179 dst_sel:DWORD dst_unused:UNUSED_PAD src0_sel:WORD_1 src1_sel:DWORD
	s_waitcnt lgkmcnt(2)
	v_mfma_f32_16x16x32_bf16 v[34:37], v[52:55], v[10:13], v[34:37]
	v_and_b32_sdwa v52, v42, v179 dst_sel:DWORD dst_unused:UNUSED_PAD src0_sel:WORD_1 src1_sel:DWORD
	v_add3_u32 v42, v42, v52, s14
	ds_read2_b64 v[52:55], v64 offset0:144 offset1:148
	s_waitcnt lgkmcnt(2)
	v_mfma_f32_16x16x32_bf16 v[34:37], v[56:59], v[14:17], v[34:37]
	ds_read2_b64 v[56:59], v64 offset0:160 offset1:164
	v_add3_u32 v41, v43, v41, s14
	v_and_b32_sdwa v43, v61, v179 dst_sel:DWORD dst_unused:UNUSED_PAD src0_sel:WORD_1 src1_sel:DWORD
	s_waitcnt lgkmcnt(2)
	v_mfma_f32_16x16x32_bf16 v[34:37], v[46:49], v[18:21], v[34:37]
	v_and_b32_sdwa v62, v60, v179 dst_sel:DWORD dst_unused:UNUSED_PAD src0_sel:WORD_1 src1_sel:DWORD
	v_add3_u32 v43, v61, v43, s14
	ds_read2_b64 v[46:49], v64 offset0:176 offset1:180
	s_waitcnt lgkmcnt(2)
	v_mfma_f32_16x16x32_bf16 v[34:37], v[52:55], v[22:25], v[34:37]
	v_add3_u32 v52, v60, v62, s14
	v_and_b32_e32 v43, 0xffff0000, v43
	v_and_b32_e32 v52, 0xffff0000, v52
	v_or_b32_sdwa v43, v43, v41 dst_sel:DWORD dst_unused:UNUSED_PAD src0_sel:DWORD src1_sel:WORD_1
	v_or_b32_sdwa v42, v52, v42 dst_sel:DWORD dst_unused:UNUSED_PAD src0_sel:DWORD src1_sel:WORD_1
	s_waitcnt vmcnt(2)
	v_lshlrev_b32_e32 v41, 16, v51
	v_lshlrev_b32_e32 v52, 16, v50
	global_store_dwordx2 v[38:39], v[42:43], off offset:32
	v_mul_f32_e32 v42, 0xbfb8aa3b, v52
	v_mul_f32_e32 v43, 0xbfb8aa3b, v41
	v_exp_f32_e32 v42, v42
	v_exp_f32_e32 v43, v43
	s_waitcnt lgkmcnt(1)
	v_mfma_f32_16x16x32_bf16 v[34:37], v[56:59], v[26:29], v[34:37]
	v_and_b32_e32 v56, 0xffff0000, v50
	v_and_b32_e32 v53, 0xffff0000, v51
	v_pk_add_f32 v[42:43], v[42:43], 1.0 op_sel_hi:[1,0]
	s_waitcnt lgkmcnt(0)
	v_mfma_f32_16x16x32_bf16 v[34:37], v[46:49], v[30:33], v[34:37]
	v_div_scale_f32 v47, s[12:13], v43, v43, v41
	v_rcp_f32_e32 v50, v47
	v_mul_f32_e32 v46, 0xbfb8aa3b, v56
	v_exp_f32_e32 v46, v46
	s_nop 3
	v_mov_b32_e32 v48, v34
	v_fma_f32 v34, -v47, v50, 1.0
	v_fmac_f32_e32 v50, v34, v50
	v_div_scale_f32 v34, vcc, v41, v43, v41
	v_mov_b32_e32 v49, v36
	v_mul_f32_e32 v36, v34, v50
	v_fma_f32 v51, -v47, v36, v34
	v_fmac_f32_e32 v36, v51, v50
	v_fma_f32 v34, -v47, v36, v34
	v_div_scale_f32 v47, s[12:13], v42, v42, v52
	v_rcp_f32_e32 v51, v47
	v_div_fmas_f32 v34, v34, v50, v36
	v_div_fixup_f32 v43, v34, v43, v41
	v_pk_mul_f32 v[48:49], v[40:41], v[48:49] op_sel_hi:[0,1]
	v_fma_f32 v34, -v47, v51, 1.0
	v_fmac_f32_e32 v51, v34, v51
	v_div_scale_f32 v34, vcc, v52, v42, v52
	v_mul_f32_e32 v36, v34, v51
	v_fma_f32 v41, -v47, v36, v34
	v_fmac_f32_e32 v36, v41, v51
	v_mul_f32_e32 v41, 0xbfb8aa3b, v53
	v_fma_f32 v34, -v47, v36, v34
	v_exp_f32_e32 v47, v41
	v_div_fmas_f32 v34, v34, v51, v36
	v_div_fixup_f32 v42, v34, v42, v52
	v_mov_b32_e32 v36, v35
	v_pk_add_f32 v[50:51], v[46:47], 1.0 op_sel_hi:[1,0]
	v_add_u32_e32 v0, 0xc000, v0
	v_div_scale_f32 v34, s[12:13], v51, v51, v53
	v_rcp_f32_e32 v41, v34
	v_div_scale_f32 v52, s[12:13], v50, v50, v56
	v_rcp_f32_e32 v58, v52
	v_fma_f32 v35, -v34, v41, 1.0
	v_pk_mul_f32 v[54:55], v[40:41], v[36:37] op_sel_hi:[0,1]
	v_fmac_f32_e32 v41, v35, v41
	v_div_scale_f32 v35, vcc, v53, v51, v53
	v_mul_f32_e32 v36, v35, v41
	v_fma_f32 v37, -v34, v36, v35
	v_fmac_f32_e32 v36, v37, v41
	v_fma_f32 v34, -v34, v36, v35
	v_div_fmas_f32 v34, v34, v41, v36
	v_div_fixup_f32 v57, v34, v51, v53
	ds_read2_b64 v[34:37], v0 offset0:96 offset1:100
	v_pk_mul_f32 v[42:43], v[48:49], v[42:43]
	ds_read2_b64 v[46:49], v0 offset0:112 offset1:116
	v_fma_f32 v41, -v52, v58, 1.0
	v_fmac_f32_e32 v58, v41, v58
	v_div_scale_f32 v41, vcc, v56, v50, v56
	v_mul_f32_e32 v51, v41, v58
	v_fma_f32 v53, -v52, v51, v41
	s_waitcnt lgkmcnt(1)
; __device__ __forceinline__ unsigned pk2(float lo, float hi) { return f2bf(lo) | (f2bf(hi) << 16); }
; __device__ __forceinline__ float bflo(unsigned u) { return __uint_as_float(u << 16); }
; __device__ __forceinline__ float bfhi(unsigned u) { return __uint_as_float(u & 0xffff0000u); }
; __device__ __forceinline__ float silu_f(float v) { return v / (1.f + __expf(-v)); }
; #define MFMA16(a, b, c) __builtin_amdgcn_mfma_f32_16x16x32_bf16(a, b, c, 0, 0, 0)
; __device__ __forceinline__ void na2_task(const Params& p_, int l, int task, unsigned char* lds) {
;     ...
;     for (int dt = 0; dt < 4; ++dt) { f32x4 o = {0.f, 0.f, 0.f, 0.f};
; #pragma unroll
;         for (int t = 0; t < 8; ++t) { const int k0 = 2 * t, k1 = 2 * t + 1, a0 = k0 / 2, c0 = k0 % 2, a1 = k1 / 2, c1 = k1 % 2;
;             const u32x2 vlo = *(const u32x2*)(VTh + (16 * dt + fr) * 520 + a0 * 64 + kst + 16 * c0 + 4 * fq), vhi = *(const u32x2*)(VTh + (16 * dt + fr) * 520 + a1 * 64 + kst + 16 * c1 + 4 * fq);
;             o = MFMA16(mk8(vlo.x, vlo.y, vhi.x, vhi.y), mk8(pp[k0][0], pp[k0][1], pp[k1][0], pp[k1][1]), o); }
;         const u32x2 gz = *(const u32x2*)(Z + qtok * DIN + 5 * DG + h * 64 + 16 * dt + 4 * fq); u32x2 ov;
;         ov.x = pk2(o[0] * inv * silu_f(bflo(gz.x)), o[1] * inv * silu_f(bfhi(gz.x))); ov.y = pk2(o[2] * inv * silu_f(bflo(gz.y)), o[3] * inv * silu_f(bfhi(gz.y)));
;         *(u32x2*)(CAT + qtok * DM + 512 + h * 64 + 16 * dt + 4 * fq) = ov; }
;     __syncthreads();
; __device__ __forceinline__ void ph_mixA(const Params& p, int l, unsigned char* lds) {
;     ...
;         for (int i = 0; i < nloc; ++i) { const int rq = (slot < 16) ? slot : 16 + i * 16 + (slot - 16);
;             na2_task(p, l, (xcd >> 2) * 256 + rq * 4 + (xcd & 3), lds); }
	v_mfma_f32_16x16x32_bf16 v[2:5], v[34:37], v[2:5], 0
	ds_read2_b64 v[34:37], v0 offset0:128 offset1:132
	v_fmac_f32_e32 v51, v53, v58
	v_fma_f32 v41, -v52, v51, v41
	v_div_fmas_f32 v41, v41, v58, v51
	v_div_fixup_f32 v56, v41, v50, v56
	ds_read2_b64 v[50:53], v0 offset0:144 offset1:148
	s_waitcnt lgkmcnt(2)
	v_mfma_f32_16x16x32_bf16 v[2:5], v[46:49], v[6:9], v[2:5]
	ds_read2_b64 v[6:9], v0 offset0:160 offset1:164
	v_pk_mul_f32 v[46:47], v[54:55], v[56:57]
	v_and_b32_sdwa v41, v43, v179 dst_sel:DWORD dst_unused:UNUSED_PAD src0_sel:WORD_1 src1_sel:DWORD
	s_waitcnt lgkmcnt(2)
	v_mfma_f32_16x16x32_bf16 v[2:5], v[34:37], v[10:13], v[2:5]
	v_and_b32_sdwa v10, v42, v179 dst_sel:DWORD dst_unused:UNUSED_PAD src0_sel:WORD_1 src1_sel:DWORD
	v_add3_u32 v34, v42, v10, s14
	ds_read2_b64 v[10:13], v0 offset0:176 offset1:180
	s_waitcnt lgkmcnt(2)
	v_mfma_f32_16x16x32_bf16 v[2:5], v[50:53], v[14:17], v[2:5]
	ds_read2_b64 v[14:17], v0 offset0:192 offset1:196
	v_and_b32_sdwa v36, v47, v179 dst_sel:DWORD dst_unused:UNUSED_PAD src0_sel:WORD_1 src1_sel:DWORD
	v_add3_u32 v35, v43, v41, s14
	s_waitcnt lgkmcnt(2)
	v_mfma_f32_16x16x32_bf16 v[2:5], v[6:9], v[18:21], v[2:5]
	ds_read2_b64 v[6:9], v0 offset0:208 offset1:212
	v_and_b32_sdwa v18, v46, v179 dst_sel:DWORD dst_unused:UNUSED_PAD src0_sel:WORD_1 src1_sel:DWORD
	v_add3_u32 v19, v47, v36, s14
	s_waitcnt lgkmcnt(2)
	v_mfma_f32_16x16x32_bf16 v[2:5], v[10:13], v[22:25], v[2:5]
	v_add3_u32 v0, v46, v18, s14
	v_and_b32_e32 v10, 0xffff0000, v19
	v_and_b32_e32 v0, 0xffff0000, v0
	s_waitcnt lgkmcnt(1)
	v_mfma_f32_16x16x32_bf16 v[2:5], v[14:17], v[26:29], v[2:5]
	v_or_b32_sdwa v11, v10, v35 dst_sel:DWORD dst_unused:UNUSED_PAD src0_sel:DWORD src1_sel:WORD_1
	v_or_b32_sdwa v10, v0, v34 dst_sel:DWORD dst_unused:UNUSED_PAD src0_sel:DWORD src1_sel:WORD_1
	s_waitcnt vmcnt(2)
	v_lshlrev_b32_e32 v0, 16, v45
	v_lshlrev_b32_e32 v12, 16, v44
	s_waitcnt lgkmcnt(0)
	v_mfma_f32_16x16x32_bf16 v[2:5], v[6:9], v[30:33], v[2:5]
	v_mul_f32_e32 v6, 0xbfb8aa3b, v12
	v_mul_f32_e32 v7, 0xbfb8aa3b, v0
	v_exp_f32_e32 v6, v6
	v_exp_f32_e32 v7, v7
	global_store_dwordx2 v[38:39], v[10:11], off offset:64
	s_nop 2
	v_mov_b32_e32 v10, v2
	v_mov_b32_e32 v11, v4
	v_pk_add_f32 v[6:7], v[6:7], 1.0 op_sel_hi:[1,0]
	v_and_b32_e32 v13, 0xffff0000, v45
	v_div_scale_f32 v9, s[12:13], v7, v7, v0
	v_rcp_f32_e32 v15, v9
	v_and_b32_e32 v14, 0xffff0000, v44
	v_mul_f32_e32 v8, 0xbfb8aa3b, v14
	v_exp_f32_e32 v8, v8
	v_fma_f32 v2, -v9, v15, 1.0
	v_fmac_f32_e32 v15, v2, v15
	v_div_scale_f32 v2, vcc, v0, v7, v0
	v_mul_f32_e32 v4, v2, v15
	v_fma_f32 v16, -v9, v4, v2
	v_fmac_f32_e32 v4, v16, v15
	v_fma_f32 v2, -v9, v4, v2
	v_div_scale_f32 v9, s[12:13], v6, v6, v12
	v_rcp_f32_e32 v16, v9
	v_div_fmas_f32 v2, v2, v15, v4
	v_div_fixup_f32 v7, v2, v7, v0
	v_pk_mul_f32 v[10:11], v[40:41], v[10:11] op_sel_hi:[0,1]
	v_fma_f32 v0, -v9, v16, 1.0
	v_fmac_f32_e32 v16, v0, v16
	v_div_scale_f32 v0, vcc, v12, v6, v12
	v_mul_f32_e32 v2, v0, v16
	v_fma_f32 v4, -v9, v2, v0
	v_fmac_f32_e32 v2, v4, v16
	v_mul_f32_e32 v4, 0xbfb8aa3b, v13
	v_fma_f32 v0, -v9, v2, v0
	v_exp_f32_e32 v9, v4
	v_div_fmas_f32 v0, v0, v16, v2
	v_div_fixup_f32 v6, v0, v6, v12
	v_mov_b32_e32 v4, v3
	v_pk_add_f32 v[8:9], v[8:9], 1.0 op_sel_hi:[1,0]
	v_pk_mul_f32 v[2:3], v[40:41], v[4:5] op_sel_hi:[0,1]
	v_div_scale_f32 v0, s[12:13], v9, v9, v13
	v_rcp_f32_e32 v12, v0
	v_pk_mul_f32 v[6:7], v[10:11], v[6:7]
	s_add_i32 s9, s3, 1
	s_cmp_lt_u32 s3, 3
	v_fma_f32 v4, -v0, v12, 1.0
	v_fmac_f32_e32 v12, v4, v12
	v_div_scale_f32 v4, vcc, v13, v9, v13
	v_mul_f32_e32 v5, v4, v12
	v_fma_f32 v10, -v0, v5, v4
	v_fmac_f32_e32 v5, v10, v12
	v_fma_f32 v0, -v0, v5, v4
	v_div_scale_f32 v4, s[12:13], v8, v8, v14
	v_rcp_f32_e32 v10, v4
	v_div_fmas_f32 v0, v0, v12, v5
	v_div_fixup_f32 v5, v0, v9, v13
	s_cselect_b64 s[12:13], -1, 0
	v_fma_f32 v0, -v4, v10, 1.0
	v_fmac_f32_e32 v10, v0, v10
	v_div_scale_f32 v0, vcc, v14, v8, v14
	v_mul_f32_e32 v9, v0, v10
	v_fma_f32 v11, -v4, v9, v0
	v_fmac_f32_e32 v9, v11, v10
	v_fma_f32 v0, -v4, v9, v0
	v_div_fmas_f32 v0, v0, v10, v9
	v_div_fixup_f32 v4, v0, v8, v14
	v_pk_mul_f32 v[2:3], v[2:3], v[4:5]
	v_and_b32_sdwa v4, v6, v179 dst_sel:DWORD dst_unused:UNUSED_PAD src0_sel:WORD_1 src1_sel:DWORD
	v_add3_u32 v4, v6, v4, s14
	v_and_b32_sdwa v5, v3, v179 dst_sel:DWORD dst_unused:UNUSED_PAD src0_sel:WORD_1 src1_sel:DWORD
	v_and_b32_sdwa v6, v2, v179 dst_sel:DWORD dst_unused:UNUSED_PAD src0_sel:WORD_1 src1_sel:DWORD
	v_and_b32_sdwa v0, v7, v179 dst_sel:DWORD dst_unused:UNUSED_PAD src0_sel:WORD_1 src1_sel:DWORD
	v_add3_u32 v3, v3, v5, s14
	v_add3_u32 v2, v2, v6, s14
	v_add3_u32 v0, v7, v0, s14
	v_and_b32_e32 v3, 0xffff0000, v3
	v_and_b32_e32 v2, 0xffff0000, v2
	s_and_b64 s[12:13], s[56:57], s[12:13]
	v_or_b32_sdwa v3, v3, v0 dst_sel:DWORD dst_unused:UNUSED_PAD src0_sel:DWORD src1_sel:WORD_1
	v_or_b32_sdwa v2, v2, v4 dst_sel:DWORD dst_unused:UNUSED_PAD src0_sel:DWORD src1_sel:WORD_1
	s_andn2_b64 vcc, exec, s[12:13]
	s_mov_b32 s3, s9
	global_store_dwordx2 v[38:39], v[2:3], off offset:96
	s_barrier
	s_cbranch_vccnz .LBB0_394
